# Y-GEMM/sample-attention -> GLU seam without grid barrier: GLU units acquire per-tile-group Z counters, conv tasks start immediately
# speedup vs baseline: 1.0047x; 1.0047x over previous
; __device__ __forceinline__ void ssm_sample_wave(float* wl  , const float* ZUS, const float* sre, const float* sim, const float* apow, const float* bbt, ...
;     const int g = task & 15, b = task >> 4, p = lane;
;     const float ar = apow[((g * 17 + 1) * 64 + p) * 2], aim = apow[((g * 17 + 1) * 64 + p) * 2 + 1];
;     float hr = sre[((size_t)b * 16 + g) * 64 + p], hi = sim[((size_t)b * 16 + g) * 64 + p];
;     const float* bp = bbt + ((size_t)g * 64 + p) * 32;
;     f32x4 bpv[8];
; #pragma unroll
;     for (int c4 = 0; c4 < 8; ++c4) bpv[c4] = *(const f32x4*)(bp + 4 * c4);
; #pragma unroll
;     for (int t = 0; t < 4; ++t) { const float* u = ZUS + (size_t)(b * 4 + t) * 256 + g * 16; float br = 0.f, bi = 0.f;
; #pragma unroll
;         for (int c4 = 0; c4 < 4; ++c4) { const f32x4 uv = *(const f32x4*)(u + 4 * c4);
; #pragma unroll
;             for (int i = 0; i < 4; ++i) { const int c = 4 * c4 + i; br += bpv[c >> 1][(c & 1) * 2] * uv[i]; bi += bpv[c >> 1][(c & 1) * 2 + 1] * uv[i]; } }
;         const float nr = ar * hr - aim * hi + br, ni = ar * hi + aim * hr + bi; hr = nr; hi = ni;
;         wl[t * 128 + p] = hr; wl[t * 128 + 64 + p] = hi; }
.LBB0_942:
	s_cmpk_gt_i32 s20, 0xff7f
	s_mov_b64 s[0:1], -1
	s_cbranch_scc0 .LBB0_965
	s_cmp_gt_i32 s20, -1
	s_waitcnt vmcnt(0)
	s_cbranch_scc0 .LBB0_945
	s_barrier
	ds_read2_b64 v[0:3], v115 offset0:6 offset1:7
	v_readlane_b32 s0, v253, 19
	v_readlane_b32 s1, v253, 20
	s_lshl_b64 s[0:1], s[0:1], 2
	s_waitcnt lgkmcnt(0)
	v_readfirstlane_b32 s3, v0
	v_readfirstlane_b32 s2, v1
	s_add_u32 s4, s3, s0
	s_addc_u32 s5, s2, s1
	v_readfirstlane_b32 s2, v3
	v_readfirstlane_b32 s3, v2
	ds_read2_b64 v[0:3], v115 offset0:20 offset1:21
	s_add_u32 s10, s3, s0
	s_addc_u32 s11, s2, s1
	v_readlane_b32 s2, v253, 56
	v_readlane_b32 s3, v253, 57
	s_waitcnt lgkmcnt(0)
	v_readfirstlane_b32 s0, v1
	v_readfirstlane_b32 s1, v0
	ds_read_b64 v[0:1], v115 offset:176
	s_add_u32 s6, s1, s2
	s_addc_u32 s7, s0, s3
	v_readfirstlane_b32 s1, v2
	v_readfirstlane_b32 s0, v3
	s_add_u32 s8, s1, s2
	s_addc_u32 s9, s0, s3
	s_waitcnt lgkmcnt(0)
	v_readfirstlane_b32 s0, v0
	v_readlane_b32 s2, v253, 58
	v_readfirstlane_b32 s1, v1
	v_readlane_b32 s3, v253, 59
	s_add_u32 s0, s0, s2
	s_addc_u32 s1, s1, s3
	s_lshl_b32 s2, s20, 3
	s_add_i32 s2, s2, s40
	s_and_b32 s12, s2, 15
	s_ashr_i32 s14, s2, 4
	s_mul_i32 s2, s12, 0x440
	v_add_lshl_u32 v0, s2, v116, 1
	v_readlane_b32 s2, v253, 17
	v_ashrrev_i32_e32 v1, 31, v0
	v_readlane_b32 s3, v253, 18
	s_ashr_i32 s15, s14, 31
	s_lshl_b64 s[16:17], s[14:15], 10
	v_lshl_add_u64 v[0:1], v[0:1], 2, s[2:3]
	s_lshl_b32 s2, s12, 6
	s_or_b32 s16, s16, s2
	global_load_dwordx2 v[48:49], v[0:1], off
	v_lshl_add_u64 v[0:1], s[16:17], 0, v[112:113]
	v_lshlrev_b64 v[50:51], 2, v[0:1]
	v_lshl_add_u64 v[0:1], s[4:5], 0, v[50:51]
	s_lshl_b32 s74, s12, 13
	s_lshl_b32 s4, s14, 2
	v_readlane_b32 s16, v253, 15
	global_load_dword v52, v[0:1], off
	v_lshl_add_u64 v[0:1], s[10:11], 0, v[50:51]
	v_readlane_b32 s17, v253, 16
	s_add_u32 s10, s16, s2
	s_addc_u32 s11, s17, 0
	s_ashr_i32 s5, s4, 31
	s_lshl_b64 s[14:15], s[4:5], 10
	s_add_u32 s14, s10, s14
	v_lshl_add_u64 v[12:13], v[118:119], 0, s[74:75]
	s_addc_u32 s15, s11, s15
	global_load_dword v53, v[0:1], off
	global_load_dwordx4 v[16:19], v[12:13], off offset:48
	global_load_dwordx4 v[20:23], v[12:13], off offset:32
	global_load_dwordx4 v[24:27], v[12:13], off offset:16
	global_load_dwordx4 v[28:31], v[12:13], off
	s_nop 0
	global_load_dwordx4 v[0:3], v[12:13], off offset:112
	global_load_dwordx4 v[4:7], v[12:13], off offset:96
	global_load_dwordx4 v[8:11], v[12:13], off offset:80
	s_nop 0
	global_load_dwordx4 v[12:15], v[12:13], off offset:64
	s_nop 0
	global_load_dwordx4 v[32:35], v161, s[14:15] offset:48
	global_load_dwordx4 v[36:39], v161, s[14:15] offset:32
	global_load_dwordx4 v[40:43], v161, s[14:15] offset:16
	global_load_dwordx4 v[44:47], v161, s[14:15]
	s_or_b32 s14, s4, 1
	s_ashr_i32 s15, s14, 31
	s_lshl_b64 s[14:15], s[14:15], 10
	s_add_u32 s14, s10, s14
	s_addc_u32 s15, s11, s15
	s_mov_b32 s3, s75
	s_waitcnt vmcnt(0)
	v_fma_f32 v54, v28, v44, 0
	v_fmac_f32_e32 v54, v30, v45
	v_fma_f32 v44, v29, v44, 0
	v_fmac_f32_e32 v54, v24, v46
	v_fmac_f32_e32 v44, v31, v45
	v_fmac_f32_e32 v54, v26, v47
	v_fmac_f32_e32 v44, v25, v46
	v_fmac_f32_e32 v54, v20, v40
	v_fmac_f32_e32 v44, v27, v47
	v_fmac_f32_e32 v54, v22, v41
	v_fmac_f32_e32 v44, v21, v40
	v_fmac_f32_e32 v54, v16, v42
	v_fmac_f32_e32 v44, v23, v41
	v_fmac_f32_e32 v54, v18, v43
	v_fmac_f32_e32 v44, v17, v42
	v_fmac_f32_e32 v54, v12, v36
	v_fmac_f32_e32 v44, v19, v43
	v_fmac_f32_e32 v54, v14, v37
	v_fmac_f32_e32 v44, v13, v36
	v_fmac_f32_e32 v54, v8, v38
	v_fmac_f32_e32 v44, v15, v37
	v_fmac_f32_e32 v54, v10, v39
	v_fmac_f32_e32 v44, v9, v38
	v_fmac_f32_e32 v54, v4, v32
	v_fmac_f32_e32 v44, v11, v39
	v_fmac_f32_e32 v54, v6, v33
	v_fmac_f32_e32 v44, v5, v32
	v_fmac_f32_e32 v54, v0, v34
	v_mul_f32_e32 v32, v49, v53
	v_fmac_f32_e32 v44, v7, v33
	v_fmac_f32_e32 v54, v2, v35
	v_fma_f32 v32, v48, v52, -v32
	v_fmac_f32_e32 v44, v1, v34
	v_add_f32_e32 v54, v32, v54
	v_mul_f32_e32 v32, v48, v53
	v_fmac_f32_e32 v44, v3, v35
	v_fmac_f32_e32 v32, v49, v52
	v_add_f32_e32 v52, v32, v44
	ds_write2st64_b32 v148, v54, v52 offset1:1
	global_load_dwordx4 v[32:35], v161, s[14:15] offset:48
	global_load_dwordx4 v[36:39], v161, s[14:15] offset:32
	global_load_dwordx4 v[40:43], v161, s[14:15] offset:16
	global_load_dwordx4 v[44:47], v161, s[14:15]
	s_or_b32 s14, s4, 2
	s_ashr_i32 s15, s14, 31
	s_lshl_b64 s[14:15], s[14:15], 10
	s_add_u32 s14, s10, s14
	s_addc_u32 s15, s11, s15
	s_waitcnt vmcnt(0)
	v_fma_f32 v53, v28, v44, 0
	v_fmac_f32_e32 v53, v30, v45
	v_fma_f32 v44, v29, v44, 0
	v_fmac_f32_e32 v53, v24, v46
	v_fmac_f32_e32 v44, v31, v45
	v_fmac_f32_e32 v53, v26, v47
	v_fmac_f32_e32 v44, v25, v46
	v_fmac_f32_e32 v53, v20, v40
	v_fmac_f32_e32 v44, v27, v47
	v_fmac_f32_e32 v53, v22, v41
	v_fmac_f32_e32 v44, v21, v40
	v_fmac_f32_e32 v53, v16, v42
	v_fmac_f32_e32 v44, v23, v41
	v_fmac_f32_e32 v53, v18, v43
	v_fmac_f32_e32 v44, v17, v42
	v_fmac_f32_e32 v53, v12, v36
	v_fmac_f32_e32 v44, v19, v43
	v_fmac_f32_e32 v53, v14, v37
	v_fmac_f32_e32 v44, v13, v36
	v_fmac_f32_e32 v53, v8, v38
	v_fmac_f32_e32 v44, v15, v37
	v_fmac_f32_e32 v53, v10, v39
	v_fmac_f32_e32 v44, v9, v38
	v_fmac_f32_e32 v53, v4, v32
	v_fmac_f32_e32 v44, v11, v39
	v_fmac_f32_e32 v53, v6, v33
	v_fmac_f32_e32 v44, v5, v32
	v_fmac_f32_e32 v53, v0, v34
	v_mul_f32_e32 v32, v49, v52
	v_fmac_f32_e32 v44, v7, v33
	v_fmac_f32_e32 v53, v2, v35
	v_fma_f32 v32, v48, v54, -v32
	v_fmac_f32_e32 v44, v1, v34
	v_add_f32_e32 v53, v32, v53
	v_mul_f32_e32 v32, v49, v54
	v_fmac_f32_e32 v44, v3, v35
	v_fmac_f32_e32 v32, v48, v52
	v_add_f32_e32 v54, v32, v44
	ds_write2st64_b32 v148, v53, v54 offset0:2 offset1:3
	global_load_dwordx4 v[32:35], v161, s[14:15] offset:48
	global_load_dwordx4 v[36:39], v161, s[14:15] offset:32
	global_load_dwordx4 v[40:43], v161, s[14:15] offset:16
	global_load_dwordx4 v[44:47], v161, s[14:15]
	s_or_b32 s14, s4, 3
	s_ashr_i32 s15, s14, 31
	s_lshl_b64 s[14:15], s[14:15], 10
	s_add_u32 s10, s10, s14
	s_addc_u32 s11, s11, s15
	s_lshl_b32 s74, s12, 5
	s_waitcnt vmcnt(0)
; __device__ __forceinline__ void ssm_sample_wave(float* wl  , const float* ZUS, const float* sre, const float* sim, const float* apow, const float* bbt, ...
;     ...
;         const float nr = ar * hr - aim * hi + br, ni = ar * hi + aim * hr + bi; hr = nr; hi = ni;
;         wl[t * 128 + p] = hr; wl[t * 128 + 64 + p] = hi; }
;     ore[((size_t)b * 16 + g) * 64 + p] = hr; oim[((size_t)b * 16 + g) * 64 + p] = hi;
;     asm volatile("s_waitcnt lgkmcnt(0)" ::: "memory");
;     const int t = lane >> 4, cp = lane & 15;
;     const float* cr = cre + ((size_t)g * 16 + cp) * 64; const float* ci = cim + ((size_t)g * 16 + cp) * 64;
;     float y = 0.f;
;     f32x4 crv[16], civ[16];
; #pragma unroll
;     for (int q4 = 0; q4 < 16; ++q4) { crv[q4] = *(const f32x4*)(cr + 4 * q4); civ[q4] = *(const f32x4*)(ci + 4 * q4); }
; #pragma unroll
;     for (int q4 = 0; q4 < 16; ++q4) { const f32x4 hr4 = *(const f32x4*)(wl + t * 128 + 4 * q4), hi4 = *(const f32x4*)(wl + t * 128 + 64 + 4 * q4);
; #pragma unroll
;         for (int i = 0; i < 4; ++i) y += crv[q4][i] * hr4[i] - civ[q4][i] * hi4[i]; }
	v_fma_f32 v52, v28, v44, 0
	v_fmac_f32_e32 v52, v30, v45
	v_fma_f32 v44, v29, v44, 0
	v_fmac_f32_e32 v52, v24, v46
	v_fmac_f32_e32 v44, v31, v45
	v_fmac_f32_e32 v52, v26, v47
	v_fmac_f32_e32 v44, v25, v46
	v_fmac_f32_e32 v52, v20, v40
	v_fmac_f32_e32 v44, v27, v47
	v_fmac_f32_e32 v52, v22, v41
	v_fmac_f32_e32 v44, v21, v40
	v_fmac_f32_e32 v52, v16, v42
	v_fmac_f32_e32 v44, v23, v41
	v_fmac_f32_e32 v52, v18, v43
	v_fmac_f32_e32 v44, v17, v42
	v_fmac_f32_e32 v52, v12, v36
	v_fmac_f32_e32 v44, v19, v43
	v_fmac_f32_e32 v52, v14, v37
	v_fmac_f32_e32 v44, v13, v36
	v_fmac_f32_e32 v52, v8, v38
	v_fmac_f32_e32 v44, v15, v37
	v_fmac_f32_e32 v52, v10, v39
	v_fmac_f32_e32 v44, v9, v38
	v_fmac_f32_e32 v52, v4, v32
	v_fmac_f32_e32 v44, v11, v39
	v_fmac_f32_e32 v52, v6, v33
	v_fmac_f32_e32 v44, v5, v32
	v_fmac_f32_e32 v52, v0, v34
	v_mul_f32_e32 v32, v49, v54
	v_fmac_f32_e32 v44, v7, v33
	v_fmac_f32_e32 v52, v2, v35
	v_fma_f32 v32, v48, v53, -v32
	v_fmac_f32_e32 v44, v1, v34
	v_add_f32_e32 v52, v32, v52
	v_mul_f32_e32 v32, v49, v53
	v_fmac_f32_e32 v44, v3, v35
	v_fmac_f32_e32 v32, v48, v54
	v_add_f32_e32 v53, v32, v44
	ds_write2st64_b32 v148, v52, v53 offset0:4 offset1:5
	global_load_dwordx4 v[32:35], v161, s[10:11] offset:48
	global_load_dwordx4 v[36:39], v161, s[10:11] offset:32
	global_load_dwordx4 v[40:43], v161, s[10:11] offset:16
	global_load_dwordx4 v[44:47], v161, s[10:11]
	v_readlane_b32 s10, v253, 23
	v_readlane_b32 s11, v253, 24
	s_waitcnt vmcnt(0)
	v_fma_f32 v28, v28, v44, 0
	v_fmac_f32_e32 v28, v30, v45
	v_fma_f32 v29, v29, v44, 0
	v_fmac_f32_e32 v28, v24, v46
	v_fmac_f32_e32 v29, v31, v45
	v_fmac_f32_e32 v28, v26, v47
	v_fmac_f32_e32 v29, v25, v46
	v_fmac_f32_e32 v28, v20, v40
	v_fmac_f32_e32 v29, v27, v47
	v_fmac_f32_e32 v28, v22, v41
	v_fmac_f32_e32 v29, v21, v40
	v_fmac_f32_e32 v28, v16, v42
	v_fmac_f32_e32 v29, v23, v41
	v_fmac_f32_e32 v28, v18, v43
	v_fmac_f32_e32 v29, v17, v42
	v_fmac_f32_e32 v28, v12, v36
	v_fmac_f32_e32 v29, v19, v43
	v_fmac_f32_e32 v28, v14, v37
	v_fmac_f32_e32 v29, v13, v36
	v_fmac_f32_e32 v28, v8, v38
	v_fmac_f32_e32 v29, v15, v37
	v_fmac_f32_e32 v28, v10, v39
	v_fmac_f32_e32 v29, v9, v38
	v_fmac_f32_e32 v28, v4, v32
	v_fmac_f32_e32 v29, v11, v39
	v_fmac_f32_e32 v28, v6, v33
	v_fmac_f32_e32 v29, v5, v32
	v_fmac_f32_e32 v28, v0, v34
	v_mul_f32_e32 v0, v49, v53
	v_fmac_f32_e32 v29, v7, v33
	v_fmac_f32_e32 v28, v2, v35
	v_fma_f32 v0, v48, v52, -v0
	v_fmac_f32_e32 v29, v1, v34
	v_add_f32_e32 v2, v0, v28
	v_mul_f32_e32 v0, v49, v52
	v_fmac_f32_e32 v29, v3, v35
	v_fmac_f32_e32 v0, v48, v53
	v_add_f32_e32 v3, v0, v29
	v_lshl_add_u64 v[0:1], s[10:11], 0, v[50:51]
	v_readlane_b32 s10, v253, 25
	v_readlane_b32 s11, v253, 26
	global_store_dword v[0:1], v2, off
	ds_write2st64_b32 v148, v2, v3 offset0:6 offset1:7
	v_lshl_add_u64 v[0:1], s[10:11], 0, v[50:51]
	global_store_dword v[0:1], v3, off
	s_waitcnt lgkmcnt(0)
	v_lshl_or_b32 v32, s12, 12, v191
	global_load_dwordx4 v[88:91], v32, s[6:7] offset:48
	global_load_dwordx4 v[104:107], v32, s[6:7] offset:32
	global_load_dwordx4 v[210:213], v32, s[6:7] offset:16
	global_load_dwordx4 v[214:217], v32, s[6:7]
	global_load_dwordx4 v[92:95], v32, s[8:9] offset:48
	global_load_dwordx4 v[108:111], v32, s[8:9] offset:32
	global_load_dwordx4 v[218:221], v32, s[8:9] offset:16
	global_load_dwordx4 v[222:225], v32, s[8:9]
	global_load_dwordx4 v[56:59], v32, s[6:7] offset:112
	global_load_dwordx4 v[72:75], v32, s[6:7] offset:96
	global_load_dwordx4 v[80:83], v32, s[6:7] offset:80
	global_load_dwordx4 v[96:99], v32, s[6:7] offset:64
	global_load_dwordx4 v[60:63], v32, s[8:9] offset:112
	global_load_dwordx4 v[76:79], v32, s[8:9] offset:96
	global_load_dwordx4 v[84:87], v32, s[8:9] offset:80
	global_load_dwordx4 v[100:103], v32, s[8:9] offset:64
	global_load_dwordx4 v[28:31], v32, s[6:7] offset:176
	global_load_dwordx4 v[40:43], v32, s[6:7] offset:160
	global_load_dwordx4 v[48:51], v32, s[6:7] offset:144
	global_load_dwordx4 v[64:67], v32, s[6:7] offset:128
	global_load_dwordx4 v[36:39], v32, s[8:9] offset:176
	global_load_dwordx4 v[44:47], v32, s[8:9] offset:160
	global_load_dwordx4 v[52:55], v32, s[8:9] offset:144
	global_load_dwordx4 v[68:71], v32, s[8:9] offset:128
	global_load_dwordx4 v[0:3], v32, s[6:7] offset:240
	global_load_dwordx4 v[8:11], v32, s[6:7] offset:224
	global_load_dwordx4 v[16:19], v32, s[6:7] offset:208
	global_load_dwordx4 v[24:27], v32, s[6:7] offset:192
	global_load_dwordx4 v[4:7], v32, s[8:9] offset:240
	global_load_dwordx4 v[12:15], v32, s[8:9] offset:224
	global_load_dwordx4 v[20:23], v32, s[8:9] offset:208
	s_nop 0
	global_load_dwordx4 v[32:35], v32, s[8:9] offset:192
	ds_read_b128 v[226:229], v192 offset:256
	ds_read_b128 v[230:233], v192
	ds_read_b128 v[234:237], v192 offset:16
	ds_read_b128 v[238:241], v192 offset:32
	ds_read_b128 v[242:245], v192 offset:48
	s_waitcnt vmcnt(24) lgkmcnt(4)
	v_mul_f32_e32 v160, v222, v226
	s_waitcnt lgkmcnt(3)
	v_fma_f32 v160, v214, v230, -v160
	v_mul_f32_e32 v214, v223, v227
	v_add_f32_e32 v160, 0, v160
	v_fma_f32 v214, v215, v231, -v214
	v_add_f32_e32 v160, v214, v160
	v_mul_f32_e32 v214, v224, v228
	v_fma_f32 v214, v216, v232, -v214
	v_add_f32_e32 v160, v214, v160
	v_mul_f32_e32 v214, v225, v229
	v_fma_f32 v214, v217, v233, -v214
	v_add_f32_e32 v160, v214, v160
	ds_read_b128 v[214:217], v192 offset:272
	s_waitcnt lgkmcnt(0)
	v_mul_f32_e32 v214, v218, v214
	v_fma_f32 v210, v210, v234, -v214
	v_add_f32_e32 v160, v210, v160
	v_mul_f32_e32 v210, v219, v215
	v_fma_f32 v210, v211, v235, -v210
	v_add_f32_e32 v160, v210, v160
	v_mul_f32_e32 v210, v220, v216
	v_fma_f32 v210, v212, v236, -v210
	v_add_f32_e32 v160, v210, v160
	v_mul_f32_e32 v210, v221, v217
	v_fma_f32 v210, v213, v237, -v210
	v_add_f32_e32 v160, v210, v160
	ds_read_b128 v[210:213], v192 offset:288
	s_waitcnt lgkmcnt(0)
; __device__ __forceinline__ void ssm_sample_wave(float* wl  , const float* ZUS, const float* sre, const float* sim, const float* apow, const float* bbt, ...
;     ...
; #pragma unroll
;     for (int q4 = 0; q4 < 16; ++q4) { const f32x4 hr4 = *(const f32x4*)(wl + t * 128 + 4 * q4), hi4 = *(const f32x4*)(wl + t * 128 + 64 + 4 * q4);
; #pragma unroll
;         for (int i = 0; i < 4; ++i) y += crv[q4][i] * hr4[i] - civ[q4][i] * hi4[i]; }
	v_mul_f32_e32 v108, v108, v210
	v_fma_f32 v104, v104, v238, -v108
	v_mul_f32_e32 v108, v109, v211
	v_add_f32_e32 v104, v104, v160
	v_fma_f32 v105, v105, v239, -v108
	v_add_f32_e32 v104, v105, v104
	v_mul_f32_e32 v105, v110, v212
	v_fma_f32 v105, v106, v240, -v105
	v_add_f32_e32 v104, v105, v104
	v_mul_f32_e32 v105, v111, v213
	v_fma_f32 v105, v107, v241, -v105
	v_add_f32_e32 v108, v105, v104
	ds_read_b128 v[104:107], v192 offset:304
	v_lshlrev_b32_e32 v160, 2, v120
	s_waitcnt lgkmcnt(0)
	v_mul_f32_e32 v92, v92, v104
	v_fma_f32 v88, v88, v242, -v92
	v_mul_f32_e32 v92, v93, v105
	v_add_f32_e32 v88, v88, v108
	v_fma_f32 v89, v89, v243, -v92
	v_add_f32_e32 v88, v89, v88
	v_mul_f32_e32 v89, v94, v106
	v_fma_f32 v89, v90, v244, -v89
	v_add_f32_e32 v88, v89, v88
	v_mul_f32_e32 v89, v95, v107
	v_fma_f32 v89, v91, v245, -v89
	v_add_f32_e32 v104, v89, v88
	ds_read_b128 v[88:91], v192 offset:64
	ds_read_b128 v[92:95], v192 offset:320
	s_waitcnt vmcnt(16) lgkmcnt(0)
	v_mul_f32_e32 v92, v100, v92
	v_fma_f32 v88, v96, v88, -v92
	v_mul_f32_e32 v92, v101, v93
	v_add_f32_e32 v88, v88, v104
	v_fma_f32 v89, v97, v89, -v92
	v_add_f32_e32 v88, v89, v88
	v_mul_f32_e32 v89, v102, v94
	v_fma_f32 v89, v98, v90, -v89
	v_add_f32_e32 v88, v89, v88
	v_mul_f32_e32 v89, v103, v95
	v_fma_f32 v89, v99, v91, -v89
	v_add_f32_e32 v96, v89, v88
	ds_read_b128 v[88:91], v192 offset:80
	ds_read_b128 v[92:95], v192 offset:336
	s_waitcnt lgkmcnt(0)
	v_mul_f32_e32 v84, v84, v92
	v_fma_f32 v80, v80, v88, -v84
	v_mul_f32_e32 v84, v85, v93
	v_add_f32_e32 v80, v80, v96
	v_fma_f32 v81, v81, v89, -v84
	v_add_f32_e32 v80, v81, v80
	v_mul_f32_e32 v81, v86, v94
	v_fma_f32 v81, v82, v90, -v81
	v_add_f32_e32 v80, v81, v80
	v_mul_f32_e32 v81, v87, v95
	v_fma_f32 v81, v83, v91, -v81
	v_add_f32_e32 v88, v81, v80
	ds_read_b128 v[80:83], v192 offset:96
	ds_read_b128 v[84:87], v192 offset:352
	s_waitcnt lgkmcnt(0)
	v_mul_f32_e32 v76, v76, v84
	v_fma_f32 v72, v72, v80, -v76
	v_mul_f32_e32 v76, v77, v85
	v_add_f32_e32 v72, v72, v88
	v_fma_f32 v73, v73, v81, -v76
	v_add_f32_e32 v72, v73, v72
	v_mul_f32_e32 v73, v78, v86
	v_fma_f32 v73, v74, v82, -v73
	v_add_f32_e32 v72, v73, v72
	v_mul_f32_e32 v73, v79, v87
	v_fma_f32 v73, v75, v83, -v73
	v_add_f32_e32 v80, v73, v72
	ds_read_b128 v[72:75], v192 offset:112
	ds_read_b128 v[76:79], v192 offset:368
	s_waitcnt lgkmcnt(0)
	v_mul_f32_e32 v60, v60, v76
	v_fma_f32 v56, v56, v72, -v60
	v_mul_f32_e32 v60, v61, v77
	v_add_f32_e32 v56, v56, v80
	v_fma_f32 v57, v57, v73, -v60
	v_add_f32_e32 v56, v57, v56
	v_mul_f32_e32 v57, v62, v78
	v_fma_f32 v57, v58, v74, -v57
	v_add_f32_e32 v56, v57, v56
	v_mul_f32_e32 v57, v63, v79
	v_fma_f32 v57, v59, v75, -v57
	v_add_f32_e32 v72, v57, v56
	ds_read_b128 v[56:59], v192 offset:128
	ds_read_b128 v[60:63], v192 offset:384
	s_waitcnt vmcnt(8) lgkmcnt(0)
	v_mul_f32_e32 v60, v68, v60
	v_fma_f32 v56, v64, v56, -v60
	v_mul_f32_e32 v60, v69, v61
	v_add_f32_e32 v56, v56, v72
	v_fma_f32 v57, v65, v57, -v60
	v_add_f32_e32 v56, v57, v56
	v_mul_f32_e32 v57, v70, v62
	v_fma_f32 v57, v66, v58, -v57
	v_add_f32_e32 v56, v57, v56
	v_mul_f32_e32 v57, v71, v63
	v_fma_f32 v57, v67, v59, -v57
	v_add_f32_e32 v64, v57, v56
	ds_read_b128 v[56:59], v192 offset:144
	ds_read_b128 v[60:63], v192 offset:400
	s_waitcnt lgkmcnt(0)
	v_mul_f32_e32 v52, v52, v60
	v_fma_f32 v48, v48, v56, -v52
	v_mul_f32_e32 v52, v53, v61
	v_add_f32_e32 v48, v48, v64
	v_fma_f32 v49, v49, v57, -v52
	v_add_f32_e32 v48, v49, v48
	v_mul_f32_e32 v49, v54, v62
	v_fma_f32 v49, v50, v58, -v49
	v_add_f32_e32 v48, v49, v48
	v_mul_f32_e32 v49, v55, v63
	v_fma_f32 v49, v51, v59, -v49
	v_add_f32_e32 v56, v49, v48
	ds_read_b128 v[48:51], v192 offset:160
	ds_read_b128 v[52:55], v192 offset:416
	s_waitcnt lgkmcnt(0)
; __device__ __forceinline__ bf16_t f2bf(float f) { return (bf16_t)(cvt_pk_bf16(f, 0.f) & 0xffffu); }
; __device__ __forceinline__ float gelu_tanh(float y) { const float u = 0.7978845608028654f * (y + 0.044715f * y * y * y); return y * (1.0f - __builtin_amdgcn_rcpf(1.0f + __expf(2.0f * u))); }
; __device__ __forceinline__ void ssm_sample_wave(float* wl  , const float* ZUS, const float* sre, const float* sim, const float* apow, const float* bbt, ...
;     ...
;     for (int q4 = 0; q4 < 16; ++q4) { const f32x4 hr4 = *(const f32x4*)(wl + t * 128 + 4 * q4), hi4 = *(const f32x4*)(wl + t * 128 + 64 + 4 * q4);
; #pragma unroll
;         for (int i = 0; i < 4; ++i) y += crv[q4][i] * hr4[i] - civ[q4][i] * hi4[i]; }
;     y += dsk[g * 16 + cp] * ZUS[(size_t)(b * 4 + t) * 256 + g * 16 + cp];
;     Z[(size_t)(MP + b * 4 + t) * 256 + g * 16 + cp] = f2bf(gelu_tanh(y));
;     asm volatile("s_waitcnt lgkmcnt(0)" ::: "memory");
	v_mul_f32_e32 v44, v44, v52
	v_fma_f32 v40, v40, v48, -v44
	v_mul_f32_e32 v44, v45, v53
	v_add_f32_e32 v40, v40, v56
	v_fma_f32 v41, v41, v49, -v44
	v_add_f32_e32 v40, v41, v40
	v_mul_f32_e32 v41, v46, v54
	v_fma_f32 v41, v42, v50, -v41
	v_add_f32_e32 v40, v41, v40
	v_mul_f32_e32 v41, v47, v55
	v_fma_f32 v41, v43, v51, -v41
	v_add_f32_e32 v48, v41, v40
	ds_read_b128 v[40:43], v192 offset:176
	ds_read_b128 v[44:47], v192 offset:432
	s_waitcnt lgkmcnt(0)
	v_mul_f32_e32 v36, v36, v44
	v_fma_f32 v28, v28, v40, -v36
	v_mul_f32_e32 v36, v37, v45
	v_add_f32_e32 v28, v28, v48
	v_fma_f32 v29, v29, v41, -v36
	v_add_f32_e32 v28, v29, v28
	v_mul_f32_e32 v29, v38, v46
	v_fma_f32 v29, v30, v42, -v29
	v_add_f32_e32 v28, v29, v28
	v_mul_f32_e32 v29, v39, v47
	v_fma_f32 v29, v31, v43, -v29
	v_add_f32_e32 v40, v29, v28
	ds_read_b128 v[28:31], v192 offset:192
	ds_read_b128 v[36:39], v192 offset:448
	s_waitcnt vmcnt(0) lgkmcnt(0)
	v_mul_f32_e32 v32, v32, v36
	v_fma_f32 v24, v24, v28, -v32
	v_mul_f32_e32 v28, v33, v37
	v_add_f32_e32 v24, v24, v40
	v_fma_f32 v25, v25, v29, -v28
	v_add_f32_e32 v24, v25, v24
	v_mul_f32_e32 v25, v34, v38
	v_fma_f32 v25, v26, v30, -v25
	v_add_f32_e32 v24, v25, v24
	v_mul_f32_e32 v25, v35, v39
	v_fma_f32 v25, v27, v31, -v25
	v_add_f32_e32 v32, v25, v24
	ds_read_b128 v[24:27], v192 offset:208
	ds_read_b128 v[28:31], v192 offset:464
	s_waitcnt lgkmcnt(0)
	v_mul_f32_e32 v20, v20, v28
	v_fma_f32 v16, v16, v24, -v20
	v_mul_f32_e32 v20, v21, v29
	v_add_f32_e32 v16, v16, v32
	v_fma_f32 v17, v17, v25, -v20
	v_add_f32_e32 v20, v17, v16
	v_pk_mul_f32 v[16:17], v[22:23], v[30:31]
	s_nop 0
	v_pk_fma_f32 v[16:17], v[18:19], v[26:27], v[16:17] neg_lo:[0,0,1] neg_hi:[0,0,1]
	s_nop 0
	v_add_f32_e32 v16, v16, v20
	v_add_f32_e32 v24, v17, v16
	ds_read_b128 v[16:19], v192 offset:224
	ds_read_b128 v[20:23], v192 offset:480
	s_waitcnt lgkmcnt(0)
	v_pk_mul_f32 v[12:13], v[12:13], v[20:21]
	s_nop 0
	v_pk_fma_f32 v[8:9], v[8:9], v[16:17], v[12:13] neg_lo:[0,0,1] neg_hi:[0,0,1]
	v_pk_mul_f32 v[14:15], v[14:15], v[22:23]
	v_add_f32_e32 v8, v8, v24
	v_pk_fma_f32 v[10:11], v[10:11], v[18:19], v[14:15] neg_lo:[0,0,1] neg_hi:[0,0,1]
	v_add_f32_e32 v8, v9, v8
	v_add_f32_e32 v8, v10, v8
	v_add_f32_e32 v16, v11, v8
	ds_read_b128 v[8:11], v192 offset:240
	ds_read_b128 v[12:15], v192 offset:496
	s_waitcnt lgkmcnt(0)
	v_pk_mul_f32 v[4:5], v[4:5], v[12:13]
	s_nop 0
	v_pk_fma_f32 v[0:1], v[0:1], v[8:9], v[4:5] neg_lo:[0,0,1] neg_hi:[0,0,1]
	v_pk_mul_f32 v[6:7], v[6:7], v[14:15]
	v_add_f32_e32 v0, v0, v16
	v_pk_fma_f32 v[2:3], v[2:3], v[10:11], v[6:7] neg_lo:[0,0,1] neg_hi:[0,0,1]
	v_add_f32_e32 v0, v1, v0
	v_add_f32_e32 v0, v2, v0
	v_add_f32_e32 v2, v3, v0
	v_or_b32_e32 v0, s2, v160
	global_load_dword v3, v0, s[0:1]
	v_add_u32_e32 v0, s4, v149
	v_ashrrev_i32_e32 v1, 31, v0
	v_lshlrev_b64 v[4:5], 10, v[0:1]
	v_lshl_add_u64 v[4:5], s[16:17], 0, v[4:5]
	v_lshl_add_u64 v[4:5], v[4:5], 0, s[2:3]
	v_lshl_add_u64 v[4:5], v[4:5], 0, v[160:161]
	global_load_dword v1, v[4:5], off
	v_add_u32_e32 v0, 0x4000, v0
	v_lshlrev_b32_e32 v160, 1, v120
	s_waitcnt vmcnt(0)
	v_fmac_f32_e32 v2, v3, v1
	v_mul_f32_e32 v1, 0x3d372713, v2
	v_mul_f32_e32 v1, v2, v1
	v_fma_f32 v1, v2, v1, v2
	v_mul_f32_e32 v1, 0x3f4c422a, v1
	v_add_f32_e32 v1, v1, v1
	v_mul_f32_e32 v1, 0x3fb8aa3b, v1
	v_exp_f32_e32 v1, v1
	s_nop 0
	v_add_f32_e32 v1, 1.0, v1
	v_rcp_f32_e32 v1, v1
	s_nop 0
	v_sub_f32_e32 v1, 1.0, v1
	v_mul_f32_e32 v1, v2, v1
	v_cvt_pk_bf16_f32 v2, v1, s0
	v_ashrrev_i32_e32 v1, 31, v0
	v_readlane_b32 s0, v253, 21
	v_lshlrev_b64 v[0:1], 9, v[0:1]
	v_readlane_b32 s1, v253, 22
	s_nop 1
	v_lshl_add_u64 v[0:1], s[0:1], 0, v[0:1]
	v_lshl_add_u64 v[0:1], v[0:1], 0, s[74:75]
	v_lshl_add_u64 v[0:1], v[0:1], 0, v[160:161]
	global_store_short v[0:1], v2, off sc0 sc1
	s_waitcnt lgkmcnt(0)
	s_mov_b64 s[0:1], 0

; #define INP(i) ((const float*)ld_ptr(pb, (i)))
; #define PHASE_END if (ph + 1 < hi) grid_barrier((unsigned*)ws, (unsigned)G, tid, (volatile LAS unsigned*)(ldsl + XBST_OFF)); } ++ph;
; __global__ void __launch_bounds__(512, 2) hybrid_fwd(Params P) {
;     ...
;             } else {
;                 const float* sinks = INP(14) + l * 8;
;                 for (int i = bid - 64; i < 128; i += G - 64) { const int task = 256 + i; MIX_TASK(task); }
;                 __syncthreads();
;             }
;         }
;         PHASE_END
.LBB0_977:
	s_add_i32 s22, s73, 2
	s_cmp_ge_i32 s22, s79
	s_waitcnt vmcnt(0)
	s_barrier
	v_readlane_b32 s0, v253, 0
	v_readlane_b32 s1, v253, 2
	s_nop 3
	s_cmp_lg_u32 s1, 0
	s_cbranch_scc1 .Lmy_ssa_noarr
	s_cmpk_lt_u32 s0, 0x40
	s_cbranch_scc1 .Lmy_ssa_noarr
	v_mov_b32_e32 v0, 0x20518
	ds_read_b64 v[0:1], v0
	s_waitcnt lgkmcnt(0)
	v_readfirstlane_b32 s2, v0
	v_readfirstlane_b32 s3, v1
	v_mov_b32_e32 v0, 0x190
	s_mov_b64 exec, 1
	v_mov_b32_e32 v1, 1
	s_nop 2
	global_atomic_add v0, v1, s[2:3]
	s_mov_b64 exec, -1
.Lmy_ssa_noarr:
	s_branch .LBB0_1031
	s_waitcnt vmcnt(0) lgkmcnt(0)
	v_cmp_eq_u32_e32 vcc, 0, v121
	s_barrier
	s_and_saveexec_b64 s[0:1], vcc
	s_cbranch_execz .LBB0_1030
	v_readlane_b32 s3, v253, 8
	s_getreg_b32 s2, hwreg(HW_REG_XCC_ID, 0, 4)
	s_and_b32 s16, s2, 15
	v_mov_b32_e32 v0, s3
	ds_read_b32 v2, v0
	v_readlane_b32 s3, v253, 9
	s_waitcnt lgkmcnt(0)
	v_cmp_ne_u32_e32 vcc, 0, v2
	v_mov_b32_e32 v0, s3
	ds_read_b32 v0, v0
	s_cbranch_vccnz .LBB0_994
	v_readlane_b32 s8, v253, 13
	v_readlane_b32 s9, v253, 14
	s_add_u32 s2, s8, 0x1000
	s_addc_u32 s3, s9, 0
	s_add_u32 s4, s8, 0x1100
	s_addc_u32 s5, s9, 0
	s_add_u32 s6, s8, 0x1200
	s_addc_u32 s7, s9, 0
	s_add_u32 s8, s8, 0x1300
	s_addc_u32 s9, s9, 0
	s_mov_b32 s17, 1
	s_branch .LBB0_982

; __device__ __forceinline__ unsigned cvt_pk_bf16(float lo, float hi) { const f32x2_t v = {lo, hi}; const bf16x2_t b = __builtin_convertvector(v, bf16x2_t); return __builtin_bit_cast(unsigned, b); }
; __device__ __forceinline__ float gelu_tanh(float y) { const float u = 0.7978845608028654f * (y + 0.044715f * y * y * y); return y * (1.0f - __builtin_amdgcn_rcpf(1.0f + __expf(2.0f * u))); }
;     __device__ __forceinline__ void operator()(const Acc& acc, const Unit& u, int wr, int wc, int fr, int fq) const {
;     ...
;             for (int m = 0; m < 4; ++m) { const int crow = u.pm * 256 + ai * 128 + wr * 64 + m * 16 + fr;
; #pragma unroll
;                 for (int bj = 0; bj < 2; ++bj)
; #pragma unroll
;                     for (int n = 0; n < 2; ++n) { const int col = bj * 128 + wc * 32 + n * 16 + fq * 4, t = col >> 4, cp = col & 15; const f32x4 v = acc[ai][bj][m][n];
;                         *(u32x2*)(Z + ((size_t)crow * 16 + t) * 256 + u.z * 16 + cp) = (u32x2){cvt_pk_bf16(gelu_tanh(v[0]), gelu_tanh(v[1])), cvt_pk_bf16(gelu_tanh(v[2]), gelu_tanh(v[3]))}; } }
.LBB0_1078:
	v_readlane_b32 s0, v253, 63
	v_readlane_b32 s1, v254, 0
	s_add_u32 s0, s0, 0x13200000
	s_addc_u32 s1, s1, 0
	v_ashrrev_i32_e32 v131, 4, v135
	s_lshl_b32 s2, s14, 8
	s_add_i32 s2, s2, s18
	v_lshl_add_u32 v135, v131, 2, s20
	v_add_u32_e32 v128, s2, v136
	v_add_u32_e32 v129, 0x80, v135
	v_ashrrev_i32_e32 v130, 4, v129
	v_ashrrev_i32_e32 v129, 31, v128
	v_lshlrev_b64 v[132:133], 13, v[128:129]
	v_mul_f32_e32 v129, 0x3d372713, v124
	v_mul_f32_e32 v129, v124, v129
	v_mul_f32_e32 v136, 0x3d372713, v125
	v_fma_f32 v129, v124, v129, v124
	v_mul_f32_e32 v136, v125, v136
	v_mul_f32_e32 v129, 0x3f4c422a, v129
	v_fma_f32 v136, v125, v136, v125
	v_add_f32_e32 v129, v129, v129
	v_mul_f32_e32 v136, 0x3f4c422a, v136
	v_mul_f32_e32 v129, 0x3fb8aa3b, v129
	v_add_f32_e32 v136, v136, v136
	v_exp_f32_e32 v129, v129
	v_mul_f32_e32 v136, 0x3fb8aa3b, v136
	v_exp_f32_e32 v137, v136
	v_mul_f32_e32 v139, 0x3d372713, v127
	v_add_f32_e32 v129, 1.0, v129
	v_rcp_f32_e32 v138, v129
	v_add_f32_e32 v129, 1.0, v137
	v_mul_f32_e32 v137, 0x3d372713, v126
	v_mul_f32_e32 v137, v126, v137
	v_fma_f32 v137, v126, v137, v126
	v_mul_f32_e32 v139, v127, v139
	v_mul_f32_e32 v137, 0x3f4c422a, v137
	v_fma_f32 v139, v127, v139, v127
	v_add_f32_e32 v137, v137, v137
	v_mul_f32_e32 v139, 0x3f4c422a, v139
	v_mul_f32_e32 v137, 0x3fb8aa3b, v137
	v_add_f32_e32 v139, v139, v139
	v_exp_f32_e32 v137, v137
	v_mul_f32_e32 v139, 0x3fb8aa3b, v139
	v_exp_f32_e32 v141, v139
	v_rcp_f32_e32 v139, v129
	v_add_f32_e32 v129, 1.0, v137
	v_rcp_f32_e32 v140, v129
	v_add_f32_e32 v129, 1.0, v141
	v_rcp_f32_e32 v141, v129
	v_pk_add_f32 v[138:139], v[138:139], 1.0 op_sel_hi:[1,0] neg_lo:[1,0] neg_hi:[1,0]
	v_ashrrev_i32_e32 v136, 4, v135
	v_pk_mul_f32 v[124:125], v[124:125], v[138:139]
	v_ashrrev_i32_e32 v137, 31, v136
	v_cvt_pk_bf16_f32 v138, v124, v125
	v_pk_add_f32 v[124:125], v[140:141], 1.0 op_sel_hi:[1,0] neg_lo:[1,0] neg_hi:[1,0]
	s_lshl_b32 s74, s12, 5
	v_pk_mul_f32 v[124:125], v[126:127], v[124:125]
	v_lshl_add_u64 v[126:127], s[0:1], 0, v[132:133]
	v_cvt_pk_bf16_f32 v139, v124, v125
	v_lshlrev_b64 v[124:125], 9, v[136:137]
	v_lshl_add_u64 v[132:133], v[126:127], 0, v[124:125]
	v_lshlrev_b32_e32 v129, 3, v131
	v_lshl_add_u64 v[132:133], v[132:133], 0, s[74:75]
	v_and_b32_e32 v160, 24, v129
	v_lshl_add_u64 v[132:133], v[132:133], 0, v[160:161]
	v_mul_f32_e32 v131, 0x3d372713, v120
	global_store_dwordx2 v[132:133], v[138:139], off sc0 sc1
	v_mul_f32_e32 v131, v120, v131
	v_mul_f32_e32 v132, 0x3d372713, v121
	v_fma_f32 v131, v120, v131, v120
	v_mul_f32_e32 v132, v121, v132
	v_mul_f32_e32 v131, 0x3f4c422a, v131
	v_fma_f32 v132, v121, v132, v121
	v_add_f32_e32 v131, v131, v131
	v_mul_f32_e32 v132, 0x3f4c422a, v132
	v_mul_f32_e32 v131, 0x3fb8aa3b, v131
	v_add_f32_e32 v132, v132, v132
	v_exp_f32_e32 v131, v131
	v_mul_f32_e32 v132, 0x3fb8aa3b, v132
	v_exp_f32_e32 v133, v132
	v_add_u32_e32 v129, 16, v135
	v_ashrrev_i32_e32 v132, 4, v129
	v_add_f32_e32 v129, 1.0, v131
	v_mul_f32_e32 v131, 0x3d372713, v122
	v_rcp_f32_e32 v136, v129
	v_add_f32_e32 v129, 1.0, v133
	v_mul_f32_e32 v131, v122, v131
	v_mul_f32_e32 v133, 0x3d372713, v123
	v_fma_f32 v131, v122, v131, v122
	v_mul_f32_e32 v133, v123, v133
	v_mul_f32_e32 v131, 0x3f4c422a, v131
	v_fma_f32 v133, v123, v133, v123
	v_add_f32_e32 v131, v131, v131
	v_mul_f32_e32 v133, 0x3f4c422a, v133
	v_mul_f32_e32 v131, 0x3fb8aa3b, v131
	v_add_f32_e32 v133, v133, v133
	v_exp_f32_e32 v131, v131
	v_mul_f32_e32 v133, 0x3fb8aa3b, v133
	v_exp_f32_e32 v133, v133
	v_rcp_f32_e32 v137, v129
	v_add_f32_e32 v129, 1.0, v131
	v_rcp_f32_e32 v138, v129
	v_add_f32_e32 v129, 1.0, v133
	v_rcp_f32_e32 v139, v129
	v_mul_f32_e32 v129, 0x3d372713, v116
	v_mul_f32_e32 v129, v116, v129
	v_mul_f32_e32 v131, 0x3d372713, v117
	v_pk_add_f32 v[136:137], v[136:137], 1.0 op_sel_hi:[1,0] neg_lo:[1,0] neg_hi:[1,0]
	v_fma_f32 v129, v116, v129, v116
	v_mul_f32_e32 v131, v117, v131
	v_pk_mul_f32 v[120:121], v[120:121], v[136:137]
	v_mul_f32_e32 v129, 0x3f4c422a, v129
	v_fma_f32 v131, v117, v131, v117
	v_cvt_pk_bf16_f32 v136, v120, v121
	v_pk_add_f32 v[120:121], v[138:139], 1.0 op_sel_hi:[1,0] neg_lo:[1,0] neg_hi:[1,0]
	v_add_f32_e32 v129, v129, v129
	v_mul_f32_e32 v131, 0x3f4c422a, v131
	v_pk_mul_f32 v[120:121], v[122:123], v[120:121]
	v_ashrrev_i32_e32 v133, 31, v132
	v_mul_f32_e32 v129, 0x3fb8aa3b, v129
	v_add_f32_e32 v131, v131, v131
	v_cvt_pk_bf16_f32 v137, v120, v121
	v_lshlrev_b64 v[120:121], 9, v[132:133]
	v_exp_f32_e32 v129, v129
	v_mul_f32_e32 v131, 0x3fb8aa3b, v131
	v_lshl_add_u64 v[122:123], v[126:127], 0, v[120:121]
	v_exp_f32_e32 v131, v131
	v_lshl_add_u64 v[122:123], v[122:123], 0, s[74:75]
	v_lshl_add_u64 v[122:123], v[122:123], 0, v[160:161]
	global_store_dwordx2 v[122:123], v[136:137], off sc0 sc1
	v_add_f32_e32 v122, 1.0, v129
	v_mul_f32_e32 v129, 0x3d372713, v118
	v_add_f32_e32 v123, 1.0, v131
	v_mul_f32_e32 v129, v118, v129
	v_mul_f32_e32 v131, 0x3d372713, v119
	v_fma_f32 v129, v118, v129, v118
	v_mul_f32_e32 v131, v119, v131
	v_mul_f32_e32 v129, 0x3f4c422a, v129
	v_fma_f32 v131, v119, v131, v119
	v_add_f32_e32 v129, v129, v129
	v_mul_f32_e32 v131, 0x3f4c422a, v131
	v_mul_f32_e32 v129, 0x3fb8aa3b, v129
	v_add_f32_e32 v131, v131, v131
	v_exp_f32_e32 v129, v129
	v_mul_f32_e32 v131, 0x3fb8aa3b, v131
	v_exp_f32_e32 v131, v131
	v_rcp_f32_e32 v122, v122
	v_rcp_f32_e32 v123, v123
	v_add_f32_e32 v129, 1.0, v129
	v_rcp_f32_e32 v132, v129
	v_add_f32_e32 v129, 1.0, v131
	v_rcp_f32_e32 v133, v129
	v_pk_add_f32 v[122:123], v[122:123], 1.0 op_sel_hi:[1,0] neg_lo:[1,0] neg_hi:[1,0]
	v_ashrrev_i32_e32 v131, 31, v130
	v_pk_mul_f32 v[116:117], v[116:117], v[122:123]
	s_movk_i32 s24, 0x7e
; __device__ __forceinline__ unsigned cvt_pk_bf16(float lo, float hi) { const f32x2_t v = {lo, hi}; const bf16x2_t b = __builtin_convertvector(v, bf16x2_t); return __builtin_bit_cast(unsigned, b); }
; __device__ __forceinline__ float gelu_tanh(float y) { const float u = 0.7978845608028654f * (y + 0.044715f * y * y * y); return y * (1.0f - __builtin_amdgcn_rcpf(1.0f + __expf(2.0f * u))); }
;     __device__ __forceinline__ void operator()(const Acc& acc, const Unit& u, int wr, int wc, int fr, int fq) const {
;     ...
;             for (int m = 0; m < 4; ++m) { const int crow = u.pm * 256 + ai * 128 + wr * 64 + m * 16 + fr;
; #pragma unroll
;                 for (int bj = 0; bj < 2; ++bj)
; #pragma unroll
;                     for (int n = 0; n < 2; ++n) { const int col = bj * 128 + wc * 32 + n * 16 + fq * 4, t = col >> 4, cp = col & 15; const f32x4 v = acc[ai][bj][m][n];
;                         *(u32x2*)(Z + ((size_t)crow * 16 + t) * 256 + u.z * 16 + cp) = (u32x2){cvt_pk_bf16(gelu_tanh(v[0]), gelu_tanh(v[1])), cvt_pk_bf16(gelu_tanh(v[2]), gelu_tanh(v[3]))}; } }
	v_cvt_pk_bf16_f32 v122, v116, v117
	v_pk_add_f32 v[116:117], v[132:133], 1.0 op_sel_hi:[1,0] neg_lo:[1,0] neg_hi:[1,0]
	s_nop 0
	v_pk_mul_f32 v[116:117], v[118:119], v[116:117]
	s_nop 0
	v_cvt_pk_bf16_f32 v123, v116, v117
	v_lshlrev_b64 v[116:117], 9, v[130:131]
	v_lshl_add_u64 v[118:119], v[126:127], 0, v[116:117]
	v_lshl_add_u64 v[118:119], v[118:119], 0, s[74:75]
	v_lshl_add_u64 v[118:119], v[118:119], 0, v[160:161]
	global_store_dwordx2 v[118:119], v[122:123], off sc0 sc1
	v_mul_f32_e32 v119, 0x3d372713, v112
	v_mul_f32_e32 v119, v112, v119
	v_mul_f32_e32 v122, 0x3d372713, v113
	v_fma_f32 v119, v112, v119, v112
	v_mul_f32_e32 v122, v113, v122
	v_mul_f32_e32 v119, 0x3f4c422a, v119
	v_fma_f32 v122, v113, v122, v113
	v_add_f32_e32 v119, v119, v119
	v_mul_f32_e32 v122, 0x3f4c422a, v122
	v_mul_f32_e32 v119, 0x3fb8aa3b, v119
	v_add_f32_e32 v122, v122, v122
	v_exp_f32_e32 v119, v119
	v_mul_f32_e32 v122, 0x3fb8aa3b, v122
	v_exp_f32_e32 v123, v122
	v_add_u32_e32 v118, 0x90, v135
	v_add_f32_e32 v119, 1.0, v119
	v_rcp_f32_e32 v122, v119
	v_add_f32_e32 v119, 1.0, v123
	v_mul_f32_e32 v123, 0x3d372713, v114
	v_mul_f32_e32 v123, v114, v123
	v_fma_f32 v123, v114, v123, v114
	v_mul_f32_e32 v123, 0x3f4c422a, v123
	v_add_f32_e32 v123, v123, v123
	v_mul_f32_e32 v123, 0x3fb8aa3b, v123
	v_exp_f32_e32 v129, v123
	v_mul_f32_e32 v123, 0x3d372713, v115
	v_mul_f32_e32 v123, v115, v123
	v_fma_f32 v123, v115, v123, v115
	v_mul_f32_e32 v123, 0x3f4c422a, v123
	v_add_f32_e32 v123, v123, v123
	v_mul_f32_e32 v123, 0x3fb8aa3b, v123
	v_exp_f32_e32 v131, v123
	v_rcp_f32_e32 v123, v119
	v_add_f32_e32 v119, 1.0, v129
	v_rcp_f32_e32 v130, v119
	v_add_f32_e32 v119, 1.0, v131
	v_rcp_f32_e32 v131, v119
	v_pk_add_f32 v[122:123], v[122:123], 1.0 op_sel_hi:[1,0] neg_lo:[1,0] neg_hi:[1,0]
	v_ashrrev_i32_e32 v118, 4, v118
	v_pk_mul_f32 v[112:113], v[112:113], v[122:123]
	v_ashrrev_i32_e32 v119, 31, v118
	v_cvt_pk_bf16_f32 v122, v112, v113
	v_pk_add_f32 v[112:113], v[130:131], 1.0 op_sel_hi:[1,0] neg_lo:[1,0] neg_hi:[1,0]
	s_nop 0
	v_pk_mul_f32 v[112:113], v[114:115], v[112:113]
	s_nop 0
	v_cvt_pk_bf16_f32 v123, v112, v113
	v_lshlrev_b64 v[112:113], 9, v[118:119]
	v_lshl_add_u64 v[114:115], v[126:127], 0, v[112:113]
	v_lshl_add_u64 v[114:115], v[114:115], 0, s[74:75]
	v_lshl_add_u64 v[114:115], v[114:115], 0, v[160:161]
	v_mul_f32_e32 v118, 0x3d372713, v108
	v_mul_f32_e32 v119, 0x3d372713, v109
	global_store_dwordx2 v[114:115], v[122:123], off sc0 sc1
	v_mul_f32_e32 v118, v108, v118
	v_mul_f32_e32 v119, v109, v119
	v_mul_f32_e32 v122, 0x3d372713, v110
	v_mul_f32_e32 v123, 0x3d372713, v111
	v_fma_f32 v118, v108, v118, v108
	v_fma_f32 v119, v109, v119, v109
	v_mul_f32_e32 v122, v110, v122
	v_mul_f32_e32 v123, v111, v123
	v_mul_f32_e32 v118, 0x3f4c422a, v118
	v_mul_f32_e32 v119, 0x3f4c422a, v119
	v_fma_f32 v122, v110, v122, v110
	v_fma_f32 v123, v111, v123, v111
	v_add_f32_e32 v118, v118, v118
	v_add_f32_e32 v119, v119, v119
	v_mul_f32_e32 v122, 0x3f4c422a, v122
	v_mul_f32_e32 v123, 0x3f4c422a, v123
	v_mul_f32_e32 v118, 0x3fb8aa3b, v118
	v_mul_f32_e32 v119, 0x3fb8aa3b, v119
	v_add_f32_e32 v122, v122, v122
	v_add_f32_e32 v123, v123, v123
	v_exp_f32_e32 v118, v118
	v_exp_f32_e32 v119, v119
	v_mul_f32_e32 v122, 0x3fb8aa3b, v122
	v_mul_f32_e32 v123, 0x3fb8aa3b, v123
	v_exp_f32_e32 v122, v122
	v_exp_f32_e32 v123, v123
	v_add_f32_e32 v118, 1.0, v118
	v_add_f32_e32 v119, 1.0, v119
	v_rcp_f32_e32 v118, v118
	v_rcp_f32_e32 v119, v119
	v_add_f32_e32 v122, 1.0, v122
	v_add_f32_e32 v123, 1.0, v123
	v_rcp_f32_e32 v122, v122
	v_rcp_f32_e32 v123, v123
	v_add_u32_e32 v114, 16, v128
	v_pk_add_f32 v[118:119], v[118:119], 1.0 op_sel_hi:[1,0] neg_lo:[1,0] neg_hi:[1,0]
	v_ashrrev_i32_e32 v115, 31, v114
	v_pk_mul_f32 v[108:109], v[108:109], v[118:119]
	v_pk_add_f32 v[118:119], v[122:123], 1.0 op_sel_hi:[1,0] neg_lo:[1,0] neg_hi:[1,0]
	v_lshlrev_b64 v[114:115], 13, v[114:115]
	v_pk_mul_f32 v[110:111], v[110:111], v[118:119]
	v_cvt_pk_bf16_f32 v108, v108, v109
	v_cvt_pk_bf16_f32 v109, v110, v111
	v_lshl_add_u64 v[110:111], s[0:1], 0, v[114:115]
	v_lshl_add_u64 v[114:115], v[110:111], 0, v[124:125]
	v_lshl_add_u64 v[114:115], v[114:115], 0, s[74:75]
	v_lshl_add_u64 v[114:115], v[114:115], 0, v[160:161]
	v_mul_f32_e32 v118, 0x3d372713, v104
	v_mul_f32_e32 v119, 0x3d372713, v105
	v_mul_f32_e32 v118, v104, v118
	v_mul_f32_e32 v119, v105, v119
	global_store_dwordx2 v[114:115], v[108:109], off sc0 sc1
	v_mul_f32_e32 v114, 0x3d372713, v106
	v_mul_f32_e32 v115, 0x3d372713, v107
	v_fma_f32 v118, v104, v118, v104
	v_fma_f32 v119, v105, v119, v105
	v_mul_f32_e32 v114, v106, v114
	v_mul_f32_e32 v115, v107, v115
	v_mul_f32_e32 v118, 0x3f4c422a, v118
	v_mul_f32_e32 v119, 0x3f4c422a, v119
	v_fma_f32 v114, v106, v114, v106
	v_fma_f32 v115, v107, v115, v107
	v_add_f32_e32 v118, v118, v118
	v_add_f32_e32 v119, v119, v119
	v_mul_f32_e32 v114, 0x3f4c422a, v114
	v_mul_f32_e32 v115, 0x3f4c422a, v115
	v_mul_f32_e32 v118, 0x3fb8aa3b, v118
	v_mul_f32_e32 v119, 0x3fb8aa3b, v119
	v_add_f32_e32 v114, v114, v114
	v_add_f32_e32 v115, v115, v115
	v_exp_f32_e32 v118, v118
	v_exp_f32_e32 v119, v119
	v_mul_f32_e32 v114, 0x3fb8aa3b, v114
	v_mul_f32_e32 v115, 0x3fb8aa3b, v115
	v_exp_f32_e32 v114, v114
	v_exp_f32_e32 v115, v115
	v_add_f32_e32 v108, 1.0, v118
	v_add_f32_e32 v109, 1.0, v119
	v_rcp_f32_e32 v108, v108
	v_rcp_f32_e32 v109, v109
	v_add_f32_e32 v114, 1.0, v114
	v_add_f32_e32 v115, 1.0, v115
	v_rcp_f32_e32 v114, v114
	v_rcp_f32_e32 v115, v115
	v_pk_add_f32 v[108:109], v[108:109], 1.0 op_sel_hi:[1,0] neg_lo:[1,0] neg_hi:[1,0]
	s_nop 0
	v_pk_mul_f32 v[104:105], v[104:105], v[108:109]
	v_pk_add_f32 v[108:109], v[114:115], 1.0 op_sel_hi:[1,0] neg_lo:[1,0] neg_hi:[1,0]
; __device__ __forceinline__ unsigned cvt_pk_bf16(float lo, float hi) { const f32x2_t v = {lo, hi}; const bf16x2_t b = __builtin_convertvector(v, bf16x2_t); return __builtin_bit_cast(unsigned, b); }
; __device__ __forceinline__ float gelu_tanh(float y) { const float u = 0.7978845608028654f * (y + 0.044715f * y * y * y); return y * (1.0f - __builtin_amdgcn_rcpf(1.0f + __expf(2.0f * u))); }
;     __device__ __forceinline__ void operator()(const Acc& acc, const Unit& u, int wr, int wc, int fr, int fq) const {
;     ...
;             for (int m = 0; m < 4; ++m) { const int crow = u.pm * 256 + ai * 128 + wr * 64 + m * 16 + fr;
; #pragma unroll
;                 for (int bj = 0; bj < 2; ++bj)
; #pragma unroll
;                     for (int n = 0; n < 2; ++n) { const int col = bj * 128 + wc * 32 + n * 16 + fq * 4, t = col >> 4, cp = col & 15; const f32x4 v = acc[ai][bj][m][n];
;                         *(u32x2*)(Z + ((size_t)crow * 16 + t) * 256 + u.z * 16 + cp) = (u32x2){cvt_pk_bf16(gelu_tanh(v[0]), gelu_tanh(v[1])), cvt_pk_bf16(gelu_tanh(v[2]), gelu_tanh(v[3]))}; } }
	v_cvt_pk_bf16_f32 v104, v104, v105
	v_pk_mul_f32 v[106:107], v[106:107], v[108:109]
	v_mul_f32_e32 v108, 0x3d372713, v100
	v_cvt_pk_bf16_f32 v105, v106, v107
	v_lshl_add_u64 v[106:107], v[110:111], 0, v[120:121]
	v_lshl_add_u64 v[106:107], v[106:107], 0, s[74:75]
	v_lshl_add_u64 v[106:107], v[106:107], 0, v[160:161]
	v_mul_f32_e32 v109, 0x3d372713, v101
	v_mul_f32_e32 v108, v100, v108
	v_mul_f32_e32 v109, v101, v109
	global_store_dwordx2 v[106:107], v[104:105], off sc0 sc1
	v_mul_f32_e32 v106, 0x3d372713, v102
	v_mul_f32_e32 v107, 0x3d372713, v103
	v_fma_f32 v108, v100, v108, v100
	v_fma_f32 v109, v101, v109, v101
	v_mul_f32_e32 v106, v102, v106
	v_mul_f32_e32 v107, v103, v107
	v_mul_f32_e32 v108, 0x3f4c422a, v108
	v_mul_f32_e32 v109, 0x3f4c422a, v109
	v_fma_f32 v106, v102, v106, v102
	v_fma_f32 v107, v103, v107, v103
	v_add_f32_e32 v108, v108, v108
	v_add_f32_e32 v109, v109, v109
	v_mul_f32_e32 v106, 0x3f4c422a, v106
	v_mul_f32_e32 v107, 0x3f4c422a, v107
	v_mul_f32_e32 v108, 0x3fb8aa3b, v108
	v_mul_f32_e32 v109, 0x3fb8aa3b, v109
	v_add_f32_e32 v106, v106, v106
	v_add_f32_e32 v107, v107, v107
	v_exp_f32_e32 v108, v108
	v_exp_f32_e32 v109, v109
	v_mul_f32_e32 v106, 0x3fb8aa3b, v106
	v_mul_f32_e32 v107, 0x3fb8aa3b, v107
	v_exp_f32_e32 v106, v106
	v_exp_f32_e32 v107, v107
	v_add_f32_e32 v104, 1.0, v108
	v_add_f32_e32 v105, 1.0, v109
	v_rcp_f32_e32 v104, v104
	v_rcp_f32_e32 v105, v105
	v_add_f32_e32 v106, 1.0, v106
	v_add_f32_e32 v107, 1.0, v107
	v_rcp_f32_e32 v106, v106
	v_rcp_f32_e32 v107, v107
	v_pk_add_f32 v[104:105], v[104:105], 1.0 op_sel_hi:[1,0] neg_lo:[1,0] neg_hi:[1,0]
	s_nop 0
	v_pk_mul_f32 v[100:101], v[100:101], v[104:105]
	v_pk_add_f32 v[104:105], v[106:107], 1.0 op_sel_hi:[1,0] neg_lo:[1,0] neg_hi:[1,0]
	v_cvt_pk_bf16_f32 v100, v100, v101
	v_pk_mul_f32 v[102:103], v[102:103], v[104:105]
	v_mul_f32_e32 v104, 0x3d372713, v96
	v_cvt_pk_bf16_f32 v101, v102, v103
	v_lshl_add_u64 v[102:103], v[110:111], 0, v[116:117]
	v_lshl_add_u64 v[102:103], v[102:103], 0, s[74:75]
	v_lshl_add_u64 v[102:103], v[102:103], 0, v[160:161]
	v_mul_f32_e32 v105, 0x3d372713, v97
	v_mul_f32_e32 v104, v96, v104
	v_mul_f32_e32 v105, v97, v105
	global_store_dwordx2 v[102:103], v[100:101], off sc0 sc1
	v_mul_f32_e32 v102, 0x3d372713, v98
	v_mul_f32_e32 v103, 0x3d372713, v99
	v_fma_f32 v104, v96, v104, v96
	v_fma_f32 v105, v97, v105, v97
	v_mul_f32_e32 v102, v98, v102
	v_mul_f32_e32 v103, v99, v103
	v_mul_f32_e32 v104, 0x3f4c422a, v104
	v_mul_f32_e32 v105, 0x3f4c422a, v105
	v_fma_f32 v102, v98, v102, v98
	v_fma_f32 v103, v99, v103, v99
	v_add_f32_e32 v104, v104, v104
	v_add_f32_e32 v105, v105, v105
	v_mul_f32_e32 v102, 0x3f4c422a, v102
	v_mul_f32_e32 v103, 0x3f4c422a, v103
	v_mul_f32_e32 v104, 0x3fb8aa3b, v104
	v_mul_f32_e32 v105, 0x3fb8aa3b, v105
	v_add_f32_e32 v102, v102, v102
	v_add_f32_e32 v103, v103, v103
	v_exp_f32_e32 v104, v104
	v_exp_f32_e32 v105, v105
	v_mul_f32_e32 v102, 0x3fb8aa3b, v102
	v_mul_f32_e32 v103, 0x3fb8aa3b, v103
	v_exp_f32_e32 v102, v102
	v_exp_f32_e32 v103, v103
	v_add_f32_e32 v100, 1.0, v104
	v_add_f32_e32 v101, 1.0, v105
	v_rcp_f32_e32 v100, v100
	v_rcp_f32_e32 v101, v101
	v_add_f32_e32 v102, 1.0, v102
	v_add_f32_e32 v103, 1.0, v103
	v_rcp_f32_e32 v102, v102
	v_rcp_f32_e32 v103, v103
	v_pk_add_f32 v[100:101], v[100:101], 1.0 op_sel_hi:[1,0] neg_lo:[1,0] neg_hi:[1,0]
	s_nop 0
	v_pk_mul_f32 v[96:97], v[96:97], v[100:101]
	v_pk_add_f32 v[100:101], v[102:103], 1.0 op_sel_hi:[1,0] neg_lo:[1,0] neg_hi:[1,0]
	v_cvt_pk_bf16_f32 v96, v96, v97
	v_pk_mul_f32 v[98:99], v[98:99], v[100:101]
	v_mul_f32_e32 v100, 0x3d372713, v94
	v_cvt_pk_bf16_f32 v97, v98, v99
	v_lshl_add_u64 v[98:99], v[110:111], 0, v[112:113]
	v_lshl_add_u64 v[98:99], v[98:99], 0, s[74:75]
	v_lshl_add_u64 v[98:99], v[98:99], 0, v[160:161]
	global_store_dwordx2 v[98:99], v[96:97], off sc0 sc1
	v_mul_f32_e32 v98, 0x3d372713, v92
	v_mul_f32_e32 v99, 0x3d372713, v93
	v_mul_f32_e32 v98, v92, v98
	v_mul_f32_e32 v99, v93, v99
	v_mul_f32_e32 v101, 0x3d372713, v95
	v_fma_f32 v98, v92, v98, v92
	v_fma_f32 v99, v93, v99, v93
	v_mul_f32_e32 v100, v94, v100
	v_mul_f32_e32 v101, v95, v101
	v_mul_f32_e32 v98, 0x3f4c422a, v98
	v_mul_f32_e32 v99, 0x3f4c422a, v99
	v_fma_f32 v100, v94, v100, v94
	v_fma_f32 v101, v95, v101, v95
	v_add_f32_e32 v98, v98, v98
	v_add_f32_e32 v99, v99, v99
	v_mul_f32_e32 v100, 0x3f4c422a, v100
	v_mul_f32_e32 v101, 0x3f4c422a, v101
	v_mul_f32_e32 v98, 0x3fb8aa3b, v98
	v_mul_f32_e32 v99, 0x3fb8aa3b, v99
	v_add_f32_e32 v100, v100, v100
	v_add_f32_e32 v101, v101, v101
	v_exp_f32_e32 v98, v98
	v_exp_f32_e32 v99, v99
	v_mul_f32_e32 v100, 0x3fb8aa3b, v100
	v_mul_f32_e32 v101, 0x3fb8aa3b, v101
	v_exp_f32_e32 v100, v100
	v_exp_f32_e32 v101, v101
	v_add_f32_e32 v98, 1.0, v98
	v_add_f32_e32 v99, 1.0, v99
	v_rcp_f32_e32 v98, v98
	v_rcp_f32_e32 v99, v99
	v_add_f32_e32 v100, 1.0, v100
	v_add_f32_e32 v101, 1.0, v101
	v_rcp_f32_e32 v100, v100
	v_rcp_f32_e32 v101, v101
	v_add_u32_e32 v96, 32, v128
	v_pk_add_f32 v[98:99], v[98:99], 1.0 op_sel_hi:[1,0] neg_lo:[1,0] neg_hi:[1,0]
	v_ashrrev_i32_e32 v97, 31, v96
	v_pk_mul_f32 v[92:93], v[92:93], v[98:99]
	v_pk_add_f32 v[98:99], v[100:101], 1.0 op_sel_hi:[1,0] neg_lo:[1,0] neg_hi:[1,0]
	v_lshlrev_b64 v[96:97], 13, v[96:97]
	v_pk_mul_f32 v[94:95], v[94:95], v[98:99]
	v_cvt_pk_bf16_f32 v92, v92, v93
	v_cvt_pk_bf16_f32 v93, v94, v95
	v_lshl_add_u64 v[94:95], s[0:1], 0, v[96:97]
	v_lshl_add_u64 v[96:97], v[94:95], 0, v[124:125]
	v_lshl_add_u64 v[96:97], v[96:97], 0, s[74:75]
	v_lshl_add_u64 v[96:97], v[96:97], 0, v[160:161]
	v_mul_f32_e32 v98, 0x3d372713, v88
	v_mul_f32_e32 v99, 0x3d372713, v89
	v_mul_f32_e32 v98, v88, v98
	v_mul_f32_e32 v99, v89, v99
; __device__ __forceinline__ unsigned cvt_pk_bf16(float lo, float hi) { const f32x2_t v = {lo, hi}; const bf16x2_t b = __builtin_convertvector(v, bf16x2_t); return __builtin_bit_cast(unsigned, b); }
; __device__ __forceinline__ float gelu_tanh(float y) { const float u = 0.7978845608028654f * (y + 0.044715f * y * y * y); return y * (1.0f - __builtin_amdgcn_rcpf(1.0f + __expf(2.0f * u))); }
;     __device__ __forceinline__ void operator()(const Acc& acc, const Unit& u, int wr, int wc, int fr, int fq) const {
;     ...
;             for (int m = 0; m < 4; ++m) { const int crow = u.pm * 256 + ai * 128 + wr * 64 + m * 16 + fr;
; #pragma unroll
;                 for (int bj = 0; bj < 2; ++bj)
; #pragma unroll
;                     for (int n = 0; n < 2; ++n) { const int col = bj * 128 + wc * 32 + n * 16 + fq * 4, t = col >> 4, cp = col & 15; const f32x4 v = acc[ai][bj][m][n];
;                         *(u32x2*)(Z + ((size_t)crow * 16 + t) * 256 + u.z * 16 + cp) = (u32x2){cvt_pk_bf16(gelu_tanh(v[0]), gelu_tanh(v[1])), cvt_pk_bf16(gelu_tanh(v[2]), gelu_tanh(v[3]))}; } }
	global_store_dwordx2 v[96:97], v[92:93], off sc0 sc1
	v_mul_f32_e32 v96, 0x3d372713, v90
	v_mul_f32_e32 v97, 0x3d372713, v91
	v_fma_f32 v98, v88, v98, v88
	v_fma_f32 v99, v89, v99, v89
	v_mul_f32_e32 v96, v90, v96
	v_mul_f32_e32 v97, v91, v97
	v_mul_f32_e32 v98, 0x3f4c422a, v98
	v_mul_f32_e32 v99, 0x3f4c422a, v99
	v_fma_f32 v96, v90, v96, v90
	v_fma_f32 v97, v91, v97, v91
	v_add_f32_e32 v98, v98, v98
	v_add_f32_e32 v99, v99, v99
	v_mul_f32_e32 v96, 0x3f4c422a, v96
	v_mul_f32_e32 v97, 0x3f4c422a, v97
	v_mul_f32_e32 v98, 0x3fb8aa3b, v98
	v_mul_f32_e32 v99, 0x3fb8aa3b, v99
	v_add_f32_e32 v96, v96, v96
	v_add_f32_e32 v97, v97, v97
	v_exp_f32_e32 v98, v98
	v_exp_f32_e32 v99, v99
	v_mul_f32_e32 v96, 0x3fb8aa3b, v96
	v_mul_f32_e32 v97, 0x3fb8aa3b, v97
	v_exp_f32_e32 v96, v96
	v_exp_f32_e32 v97, v97
	v_add_f32_e32 v92, 1.0, v98
	v_add_f32_e32 v93, 1.0, v99
	v_rcp_f32_e32 v92, v92
	v_rcp_f32_e32 v93, v93
	v_add_f32_e32 v96, 1.0, v96
	v_add_f32_e32 v97, 1.0, v97
	v_rcp_f32_e32 v96, v96
	v_rcp_f32_e32 v97, v97
	v_pk_add_f32 v[92:93], v[92:93], 1.0 op_sel_hi:[1,0] neg_lo:[1,0] neg_hi:[1,0]
	s_nop 0
	v_pk_mul_f32 v[88:89], v[88:89], v[92:93]
	v_pk_add_f32 v[92:93], v[96:97], 1.0 op_sel_hi:[1,0] neg_lo:[1,0] neg_hi:[1,0]
	v_cvt_pk_bf16_f32 v88, v88, v89
	v_pk_mul_f32 v[90:91], v[90:91], v[92:93]
	v_mul_f32_e32 v92, 0x3d372713, v84
	v_cvt_pk_bf16_f32 v89, v90, v91
	v_lshl_add_u64 v[90:91], v[94:95], 0, v[120:121]
	v_lshl_add_u64 v[90:91], v[90:91], 0, s[74:75]
	v_lshl_add_u64 v[90:91], v[90:91], 0, v[160:161]
	v_mul_f32_e32 v93, 0x3d372713, v85
	v_mul_f32_e32 v92, v84, v92
	v_mul_f32_e32 v93, v85, v93
	global_store_dwordx2 v[90:91], v[88:89], off sc0 sc1
	v_mul_f32_e32 v90, 0x3d372713, v86
	v_mul_f32_e32 v91, 0x3d372713, v87
	v_fma_f32 v92, v84, v92, v84
	v_fma_f32 v93, v85, v93, v85
	v_mul_f32_e32 v90, v86, v90
	v_mul_f32_e32 v91, v87, v91
	v_mul_f32_e32 v92, 0x3f4c422a, v92
	v_mul_f32_e32 v93, 0x3f4c422a, v93
	v_fma_f32 v90, v86, v90, v86
	v_fma_f32 v91, v87, v91, v87
	v_add_f32_e32 v92, v92, v92
	v_add_f32_e32 v93, v93, v93
	v_mul_f32_e32 v90, 0x3f4c422a, v90
	v_mul_f32_e32 v91, 0x3f4c422a, v91
	v_mul_f32_e32 v92, 0x3fb8aa3b, v92
	v_mul_f32_e32 v93, 0x3fb8aa3b, v93
	v_add_f32_e32 v90, v90, v90
	v_add_f32_e32 v91, v91, v91
	v_exp_f32_e32 v92, v92
	v_exp_f32_e32 v93, v93
	v_mul_f32_e32 v90, 0x3fb8aa3b, v90
	v_mul_f32_e32 v91, 0x3fb8aa3b, v91
	v_exp_f32_e32 v90, v90
	v_exp_f32_e32 v91, v91
	v_add_f32_e32 v88, 1.0, v92
	v_add_f32_e32 v89, 1.0, v93
	v_rcp_f32_e32 v88, v88
	v_rcp_f32_e32 v89, v89
	v_add_f32_e32 v90, 1.0, v90
	v_add_f32_e32 v91, 1.0, v91
	v_rcp_f32_e32 v90, v90
	v_rcp_f32_e32 v91, v91
	v_pk_add_f32 v[88:89], v[88:89], 1.0 op_sel_hi:[1,0] neg_lo:[1,0] neg_hi:[1,0]
	s_nop 0
	v_pk_mul_f32 v[84:85], v[84:85], v[88:89]
	v_pk_add_f32 v[88:89], v[90:91], 1.0 op_sel_hi:[1,0] neg_lo:[1,0] neg_hi:[1,0]
	v_cvt_pk_bf16_f32 v84, v84, v85
	v_pk_mul_f32 v[86:87], v[86:87], v[88:89]
	v_mul_f32_e32 v88, 0x3d372713, v80
	v_cvt_pk_bf16_f32 v85, v86, v87
	v_lshl_add_u64 v[86:87], v[94:95], 0, v[116:117]
	v_lshl_add_u64 v[86:87], v[86:87], 0, s[74:75]
	v_lshl_add_u64 v[86:87], v[86:87], 0, v[160:161]
	v_mul_f32_e32 v89, 0x3d372713, v81
	v_mul_f32_e32 v88, v80, v88
	v_mul_f32_e32 v89, v81, v89
	global_store_dwordx2 v[86:87], v[84:85], off sc0 sc1
	v_mul_f32_e32 v86, 0x3d372713, v82
	v_mul_f32_e32 v87, 0x3d372713, v83
	v_fma_f32 v88, v80, v88, v80
	v_fma_f32 v89, v81, v89, v81
	v_mul_f32_e32 v86, v82, v86
	v_mul_f32_e32 v87, v83, v87
	v_mul_f32_e32 v88, 0x3f4c422a, v88
	v_mul_f32_e32 v89, 0x3f4c422a, v89
	v_fma_f32 v86, v82, v86, v82
	v_fma_f32 v87, v83, v87, v83
	v_add_f32_e32 v88, v88, v88
	v_add_f32_e32 v89, v89, v89
	v_mul_f32_e32 v86, 0x3f4c422a, v86
	v_mul_f32_e32 v87, 0x3f4c422a, v87
	v_mul_f32_e32 v88, 0x3fb8aa3b, v88
	v_mul_f32_e32 v89, 0x3fb8aa3b, v89
	v_add_f32_e32 v86, v86, v86
	v_add_f32_e32 v87, v87, v87
	v_exp_f32_e32 v88, v88
	v_exp_f32_e32 v89, v89
	v_mul_f32_e32 v86, 0x3fb8aa3b, v86
	v_mul_f32_e32 v87, 0x3fb8aa3b, v87
	v_exp_f32_e32 v86, v86
	v_exp_f32_e32 v87, v87
	v_add_f32_e32 v84, 1.0, v88
	v_add_f32_e32 v85, 1.0, v89
	v_rcp_f32_e32 v84, v84
	v_rcp_f32_e32 v85, v85
	v_add_f32_e32 v86, 1.0, v86
	v_add_f32_e32 v87, 1.0, v87
	v_rcp_f32_e32 v86, v86
	v_rcp_f32_e32 v87, v87
	v_pk_add_f32 v[84:85], v[84:85], 1.0 op_sel_hi:[1,0] neg_lo:[1,0] neg_hi:[1,0]
	s_nop 0
	v_pk_mul_f32 v[80:81], v[80:81], v[84:85]
	v_pk_add_f32 v[84:85], v[86:87], 1.0 op_sel_hi:[1,0] neg_lo:[1,0] neg_hi:[1,0]
	v_cvt_pk_bf16_f32 v80, v80, v81
	v_pk_mul_f32 v[82:83], v[82:83], v[84:85]
	v_mul_f32_e32 v84, 0x3d372713, v78
	v_cvt_pk_bf16_f32 v81, v82, v83
	v_lshl_add_u64 v[82:83], v[94:95], 0, v[112:113]
	v_lshl_add_u64 v[82:83], v[82:83], 0, s[74:75]
	v_lshl_add_u64 v[82:83], v[82:83], 0, v[160:161]
	global_store_dwordx2 v[82:83], v[80:81], off sc0 sc1
	v_mul_f32_e32 v82, 0x3d372713, v76
	v_mul_f32_e32 v83, 0x3d372713, v77
	v_mul_f32_e32 v82, v76, v82
	v_mul_f32_e32 v83, v77, v83
	v_mul_f32_e32 v85, 0x3d372713, v79
	v_fma_f32 v82, v76, v82, v76
	v_fma_f32 v83, v77, v83, v77
	v_mul_f32_e32 v84, v78, v84
	v_mul_f32_e32 v85, v79, v85
	v_mul_f32_e32 v82, 0x3f4c422a, v82
	v_mul_f32_e32 v83, 0x3f4c422a, v83
	v_fma_f32 v84, v78, v84, v78
	v_fma_f32 v85, v79, v85, v79
	v_add_f32_e32 v82, v82, v82
	v_add_f32_e32 v83, v83, v83
	v_mul_f32_e32 v84, 0x3f4c422a, v84
	v_mul_f32_e32 v85, 0x3f4c422a, v85
	v_mul_f32_e32 v82, 0x3fb8aa3b, v82
	v_mul_f32_e32 v83, 0x3fb8aa3b, v83
	v_add_f32_e32 v84, v84, v84
	v_add_f32_e32 v85, v85, v85
	v_exp_f32_e32 v82, v82
	v_exp_f32_e32 v83, v83
	v_mul_f32_e32 v84, 0x3fb8aa3b, v84
	v_mul_f32_e32 v85, 0x3fb8aa3b, v85
	v_exp_f32_e32 v84, v84
	v_exp_f32_e32 v85, v85
; __device__ __forceinline__ unsigned cvt_pk_bf16(float lo, float hi) { const f32x2_t v = {lo, hi}; const bf16x2_t b = __builtin_convertvector(v, bf16x2_t); return __builtin_bit_cast(unsigned, b); }
; __device__ __forceinline__ float gelu_tanh(float y) { const float u = 0.7978845608028654f * (y + 0.044715f * y * y * y); return y * (1.0f - __builtin_amdgcn_rcpf(1.0f + __expf(2.0f * u))); }
;     __device__ __forceinline__ void operator()(const Acc& acc, const Unit& u, int wr, int wc, int fr, int fq) const {
;     ...
;             for (int m = 0; m < 4; ++m) { const int crow = u.pm * 256 + ai * 128 + wr * 64 + m * 16 + fr;
; #pragma unroll
;                 for (int bj = 0; bj < 2; ++bj)
; #pragma unroll
;                     for (int n = 0; n < 2; ++n) { const int col = bj * 128 + wc * 32 + n * 16 + fq * 4, t = col >> 4, cp = col & 15; const f32x4 v = acc[ai][bj][m][n];
;                         *(u32x2*)(Z + ((size_t)crow * 16 + t) * 256 + u.z * 16 + cp) = (u32x2){cvt_pk_bf16(gelu_tanh(v[0]), gelu_tanh(v[1])), cvt_pk_bf16(gelu_tanh(v[2]), gelu_tanh(v[3]))}; } }
	v_add_f32_e32 v82, 1.0, v82
	v_add_f32_e32 v83, 1.0, v83
	v_rcp_f32_e32 v82, v82
	v_rcp_f32_e32 v83, v83
	v_add_f32_e32 v84, 1.0, v84
	v_add_f32_e32 v85, 1.0, v85
	v_rcp_f32_e32 v84, v84
	v_rcp_f32_e32 v85, v85
	v_add_u32_e32 v80, 48, v128
	v_pk_add_f32 v[82:83], v[82:83], 1.0 op_sel_hi:[1,0] neg_lo:[1,0] neg_hi:[1,0]
	v_ashrrev_i32_e32 v81, 31, v80
	v_pk_mul_f32 v[76:77], v[76:77], v[82:83]
	v_pk_add_f32 v[82:83], v[84:85], 1.0 op_sel_hi:[1,0] neg_lo:[1,0] neg_hi:[1,0]
	v_lshlrev_b64 v[80:81], 13, v[80:81]
	v_pk_mul_f32 v[78:79], v[78:79], v[82:83]
	v_cvt_pk_bf16_f32 v76, v76, v77
	v_cvt_pk_bf16_f32 v77, v78, v79
	v_lshl_add_u64 v[78:79], s[0:1], 0, v[80:81]
	v_lshl_add_u64 v[80:81], v[78:79], 0, v[124:125]
	v_lshl_add_u64 v[80:81], v[80:81], 0, s[74:75]
	v_lshl_add_u64 v[80:81], v[80:81], 0, v[160:161]
	v_mul_f32_e32 v82, 0x3d372713, v72
	v_mul_f32_e32 v83, 0x3d372713, v73
	v_mul_f32_e32 v82, v72, v82
	v_mul_f32_e32 v83, v73, v83
	global_store_dwordx2 v[80:81], v[76:77], off sc0 sc1
	v_mul_f32_e32 v80, 0x3d372713, v74
	v_mul_f32_e32 v81, 0x3d372713, v75
	v_fma_f32 v82, v72, v82, v72
	v_fma_f32 v83, v73, v83, v73
	v_mul_f32_e32 v80, v74, v80
	v_mul_f32_e32 v81, v75, v81
	v_mul_f32_e32 v82, 0x3f4c422a, v82
	v_mul_f32_e32 v83, 0x3f4c422a, v83
	v_fma_f32 v80, v74, v80, v74
	v_fma_f32 v81, v75, v81, v75
	v_add_f32_e32 v82, v82, v82
	v_add_f32_e32 v83, v83, v83
	v_mul_f32_e32 v80, 0x3f4c422a, v80
	v_mul_f32_e32 v81, 0x3f4c422a, v81
	v_mul_f32_e32 v82, 0x3fb8aa3b, v82
	v_mul_f32_e32 v83, 0x3fb8aa3b, v83
	v_add_f32_e32 v80, v80, v80
	v_add_f32_e32 v81, v81, v81
	v_exp_f32_e32 v82, v82
	v_exp_f32_e32 v83, v83
	v_mul_f32_e32 v80, 0x3fb8aa3b, v80
	v_mul_f32_e32 v81, 0x3fb8aa3b, v81
	v_exp_f32_e32 v80, v80
	v_exp_f32_e32 v81, v81
	v_add_f32_e32 v76, 1.0, v82
	v_add_f32_e32 v77, 1.0, v83
	v_rcp_f32_e32 v76, v76
	v_rcp_f32_e32 v77, v77
	v_add_f32_e32 v80, 1.0, v80
	v_add_f32_e32 v81, 1.0, v81
	v_rcp_f32_e32 v80, v80
	v_rcp_f32_e32 v81, v81
	v_pk_add_f32 v[76:77], v[76:77], 1.0 op_sel_hi:[1,0] neg_lo:[1,0] neg_hi:[1,0]
	s_nop 0
	v_pk_mul_f32 v[72:73], v[72:73], v[76:77]
	v_pk_add_f32 v[76:77], v[80:81], 1.0 op_sel_hi:[1,0] neg_lo:[1,0] neg_hi:[1,0]
	v_cvt_pk_bf16_f32 v72, v72, v73
	v_pk_mul_f32 v[74:75], v[74:75], v[76:77]
	v_mul_f32_e32 v76, 0x3d372713, v68
	v_cvt_pk_bf16_f32 v73, v74, v75
	v_lshl_add_u64 v[74:75], v[78:79], 0, v[120:121]
	v_lshl_add_u64 v[74:75], v[74:75], 0, s[74:75]
	v_lshl_add_u64 v[74:75], v[74:75], 0, v[160:161]
	v_mul_f32_e32 v77, 0x3d372713, v69
	v_mul_f32_e32 v76, v68, v76
	v_mul_f32_e32 v77, v69, v77
	global_store_dwordx2 v[74:75], v[72:73], off sc0 sc1
	v_mul_f32_e32 v74, 0x3d372713, v70
	v_mul_f32_e32 v75, 0x3d372713, v71
	v_fma_f32 v76, v68, v76, v68
	v_fma_f32 v77, v69, v77, v69
	v_mul_f32_e32 v74, v70, v74
	v_mul_f32_e32 v75, v71, v75
	v_mul_f32_e32 v76, 0x3f4c422a, v76
	v_mul_f32_e32 v77, 0x3f4c422a, v77
	v_fma_f32 v74, v70, v74, v70
	v_fma_f32 v75, v71, v75, v71
	v_add_f32_e32 v76, v76, v76
	v_add_f32_e32 v77, v77, v77
	v_mul_f32_e32 v74, 0x3f4c422a, v74
	v_mul_f32_e32 v75, 0x3f4c422a, v75
	v_mul_f32_e32 v76, 0x3fb8aa3b, v76
	v_mul_f32_e32 v77, 0x3fb8aa3b, v77
	v_add_f32_e32 v74, v74, v74
	v_add_f32_e32 v75, v75, v75
	v_exp_f32_e32 v76, v76
	v_exp_f32_e32 v77, v77
	v_mul_f32_e32 v74, 0x3fb8aa3b, v74
	v_mul_f32_e32 v75, 0x3fb8aa3b, v75
	v_exp_f32_e32 v74, v74
	v_exp_f32_e32 v75, v75
	v_add_f32_e32 v72, 1.0, v76
	v_add_f32_e32 v73, 1.0, v77
	v_rcp_f32_e32 v72, v72
	v_rcp_f32_e32 v73, v73
	v_add_f32_e32 v74, 1.0, v74
	v_add_f32_e32 v75, 1.0, v75
	v_rcp_f32_e32 v74, v74
	v_rcp_f32_e32 v75, v75
	v_pk_add_f32 v[72:73], v[72:73], 1.0 op_sel_hi:[1,0] neg_lo:[1,0] neg_hi:[1,0]
	s_nop 0
	v_pk_mul_f32 v[68:69], v[68:69], v[72:73]
	v_pk_add_f32 v[72:73], v[74:75], 1.0 op_sel_hi:[1,0] neg_lo:[1,0] neg_hi:[1,0]
	v_cvt_pk_bf16_f32 v68, v68, v69
	v_pk_mul_f32 v[70:71], v[70:71], v[72:73]
	v_mul_f32_e32 v72, 0x3d372713, v64
	v_cvt_pk_bf16_f32 v69, v70, v71
	v_lshl_add_u64 v[70:71], v[78:79], 0, v[116:117]
	v_lshl_add_u64 v[70:71], v[70:71], 0, s[74:75]
	v_lshl_add_u64 v[70:71], v[70:71], 0, v[160:161]
	v_mul_f32_e32 v73, 0x3d372713, v65
	v_mul_f32_e32 v72, v64, v72
	v_mul_f32_e32 v73, v65, v73
	global_store_dwordx2 v[70:71], v[68:69], off sc0 sc1
	v_mul_f32_e32 v70, 0x3d372713, v66
	v_mul_f32_e32 v71, 0x3d372713, v67
	v_fma_f32 v72, v64, v72, v64
	v_fma_f32 v73, v65, v73, v65
	v_mul_f32_e32 v70, v66, v70
	v_mul_f32_e32 v71, v67, v71
	v_mul_f32_e32 v72, 0x3f4c422a, v72
	v_mul_f32_e32 v73, 0x3f4c422a, v73
	v_fma_f32 v70, v66, v70, v66
	v_fma_f32 v71, v67, v71, v67
	v_add_f32_e32 v72, v72, v72
	v_add_f32_e32 v73, v73, v73
	v_mul_f32_e32 v70, 0x3f4c422a, v70
	v_mul_f32_e32 v71, 0x3f4c422a, v71
	v_mul_f32_e32 v72, 0x3fb8aa3b, v72
	v_mul_f32_e32 v73, 0x3fb8aa3b, v73
	v_add_f32_e32 v70, v70, v70
	v_add_f32_e32 v71, v71, v71
	v_exp_f32_e32 v72, v72
	v_exp_f32_e32 v73, v73
	v_mul_f32_e32 v70, 0x3fb8aa3b, v70
	v_mul_f32_e32 v71, 0x3fb8aa3b, v71
	v_exp_f32_e32 v70, v70
	v_exp_f32_e32 v71, v71
	v_add_f32_e32 v68, 1.0, v72
	v_add_f32_e32 v69, 1.0, v73
	v_rcp_f32_e32 v68, v68
	v_rcp_f32_e32 v69, v69
	v_add_f32_e32 v70, 1.0, v70
	v_add_f32_e32 v71, 1.0, v71
	v_rcp_f32_e32 v70, v70
	v_rcp_f32_e32 v71, v71
	v_pk_add_f32 v[68:69], v[68:69], 1.0 op_sel_hi:[1,0] neg_lo:[1,0] neg_hi:[1,0]
	s_nop 0
	v_pk_mul_f32 v[64:65], v[64:65], v[68:69]
	v_pk_add_f32 v[68:69], v[70:71], 1.0 op_sel_hi:[1,0] neg_lo:[1,0] neg_hi:[1,0]
	v_cvt_pk_bf16_f32 v64, v64, v65
	v_pk_mul_f32 v[66:67], v[66:67], v[68:69]
	v_mul_f32_e32 v68, 0x3d372713, v62
	v_cvt_pk_bf16_f32 v65, v66, v67
	v_lshl_add_u64 v[66:67], v[78:79], 0, v[112:113]
	v_lshl_add_u64 v[66:67], v[66:67], 0, s[74:75]
; __device__ __forceinline__ unsigned cvt_pk_bf16(float lo, float hi) { const f32x2_t v = {lo, hi}; const bf16x2_t b = __builtin_convertvector(v, bf16x2_t); return __builtin_bit_cast(unsigned, b); }
; __device__ __forceinline__ float gelu_tanh(float y) { const float u = 0.7978845608028654f * (y + 0.044715f * y * y * y); return y * (1.0f - __builtin_amdgcn_rcpf(1.0f + __expf(2.0f * u))); }
;     __device__ __forceinline__ void operator()(const Acc& acc, const Unit& u, int wr, int wc, int fr, int fq) const {
;     ...
;             for (int m = 0; m < 4; ++m) { const int crow = u.pm * 256 + ai * 128 + wr * 64 + m * 16 + fr;
; #pragma unroll
;                 for (int bj = 0; bj < 2; ++bj)
; #pragma unroll
;                     for (int n = 0; n < 2; ++n) { const int col = bj * 128 + wc * 32 + n * 16 + fq * 4, t = col >> 4, cp = col & 15; const f32x4 v = acc[ai][bj][m][n];
;                         *(u32x2*)(Z + ((size_t)crow * 16 + t) * 256 + u.z * 16 + cp) = (u32x2){cvt_pk_bf16(gelu_tanh(v[0]), gelu_tanh(v[1])), cvt_pk_bf16(gelu_tanh(v[2]), gelu_tanh(v[3]))}; } }
	v_lshl_add_u64 v[66:67], v[66:67], 0, v[160:161]
	global_store_dwordx2 v[66:67], v[64:65], off sc0 sc1
	v_mul_f32_e32 v66, 0x3d372713, v60
	v_mul_f32_e32 v67, 0x3d372713, v61
	v_mul_f32_e32 v66, v60, v66
	v_mul_f32_e32 v67, v61, v67
	v_mul_f32_e32 v69, 0x3d372713, v63
	v_fma_f32 v66, v60, v66, v60
	v_fma_f32 v67, v61, v67, v61
	v_mul_f32_e32 v68, v62, v68
	v_mul_f32_e32 v69, v63, v69
	v_mul_f32_e32 v66, 0x3f4c422a, v66
	v_mul_f32_e32 v67, 0x3f4c422a, v67
	v_fma_f32 v68, v62, v68, v62
	v_fma_f32 v69, v63, v69, v63
	v_add_f32_e32 v66, v66, v66
	v_add_f32_e32 v67, v67, v67
	v_mul_f32_e32 v68, 0x3f4c422a, v68
	v_mul_f32_e32 v69, 0x3f4c422a, v69
	v_mul_f32_e32 v66, 0x3fb8aa3b, v66
	v_mul_f32_e32 v67, 0x3fb8aa3b, v67
	v_add_f32_e32 v68, v68, v68
	v_add_f32_e32 v69, v69, v69
	v_exp_f32_e32 v66, v66
	v_exp_f32_e32 v67, v67
	v_mul_f32_e32 v68, 0x3fb8aa3b, v68
	v_mul_f32_e32 v69, 0x3fb8aa3b, v69
	v_exp_f32_e32 v68, v68
	v_exp_f32_e32 v69, v69
	v_add_f32_e32 v66, 1.0, v66
	v_add_f32_e32 v67, 1.0, v67
	v_rcp_f32_e32 v66, v66
	v_rcp_f32_e32 v67, v67
	v_add_f32_e32 v68, 1.0, v68
	v_add_f32_e32 v69, 1.0, v69
	v_rcp_f32_e32 v68, v68
	v_rcp_f32_e32 v69, v69
	v_add_u32_e32 v64, 0x80, v128
	v_pk_add_f32 v[66:67], v[66:67], 1.0 op_sel_hi:[1,0] neg_lo:[1,0] neg_hi:[1,0]
	v_ashrrev_i32_e32 v65, 31, v64
	v_pk_mul_f32 v[60:61], v[60:61], v[66:67]
	v_pk_add_f32 v[66:67], v[68:69], 1.0 op_sel_hi:[1,0] neg_lo:[1,0] neg_hi:[1,0]
	v_lshlrev_b64 v[64:65], 13, v[64:65]
	v_pk_mul_f32 v[62:63], v[62:63], v[66:67]
	v_cvt_pk_bf16_f32 v60, v60, v61
	v_cvt_pk_bf16_f32 v61, v62, v63
	v_lshl_add_u64 v[62:63], s[0:1], 0, v[64:65]
	v_lshl_add_u64 v[64:65], v[62:63], 0, v[124:125]
	v_lshl_add_u64 v[64:65], v[64:65], 0, s[74:75]
	v_lshl_add_u64 v[64:65], v[64:65], 0, v[160:161]
	v_mul_f32_e32 v66, 0x3d372713, v56
	v_mul_f32_e32 v67, 0x3d372713, v57
	v_mul_f32_e32 v66, v56, v66
	v_mul_f32_e32 v67, v57, v67
	global_store_dwordx2 v[64:65], v[60:61], off sc0 sc1
	v_mul_f32_e32 v64, 0x3d372713, v58
	v_mul_f32_e32 v65, 0x3d372713, v59
	v_fma_f32 v66, v56, v66, v56
	v_fma_f32 v67, v57, v67, v57
	v_mul_f32_e32 v64, v58, v64
	v_mul_f32_e32 v65, v59, v65
	v_mul_f32_e32 v66, 0x3f4c422a, v66
	v_mul_f32_e32 v67, 0x3f4c422a, v67
	v_fma_f32 v64, v58, v64, v58
	v_fma_f32 v65, v59, v65, v59
	v_add_f32_e32 v66, v66, v66
	v_add_f32_e32 v67, v67, v67
	v_mul_f32_e32 v64, 0x3f4c422a, v64
	v_mul_f32_e32 v65, 0x3f4c422a, v65
	v_mul_f32_e32 v66, 0x3fb8aa3b, v66
	v_mul_f32_e32 v67, 0x3fb8aa3b, v67
	v_add_f32_e32 v64, v64, v64
	v_add_f32_e32 v65, v65, v65
	v_exp_f32_e32 v66, v66
	v_exp_f32_e32 v67, v67
	v_mul_f32_e32 v64, 0x3fb8aa3b, v64
	v_mul_f32_e32 v65, 0x3fb8aa3b, v65
	v_exp_f32_e32 v64, v64
	v_exp_f32_e32 v65, v65
	v_add_f32_e32 v60, 1.0, v66
	v_add_f32_e32 v61, 1.0, v67
	v_rcp_f32_e32 v60, v60
	v_rcp_f32_e32 v61, v61
	v_add_f32_e32 v64, 1.0, v64
	v_add_f32_e32 v65, 1.0, v65
	v_rcp_f32_e32 v64, v64
	v_rcp_f32_e32 v65, v65
	v_pk_add_f32 v[60:61], v[60:61], 1.0 op_sel_hi:[1,0] neg_lo:[1,0] neg_hi:[1,0]
	s_nop 0
	v_pk_mul_f32 v[56:57], v[56:57], v[60:61]
	v_pk_add_f32 v[60:61], v[64:65], 1.0 op_sel_hi:[1,0] neg_lo:[1,0] neg_hi:[1,0]
	v_cvt_pk_bf16_f32 v56, v56, v57
	v_pk_mul_f32 v[58:59], v[58:59], v[60:61]
	v_mul_f32_e32 v60, 0x3d372713, v52
	v_cvt_pk_bf16_f32 v57, v58, v59
	v_lshl_add_u64 v[58:59], v[62:63], 0, v[120:121]
	v_lshl_add_u64 v[58:59], v[58:59], 0, s[74:75]
	v_lshl_add_u64 v[58:59], v[58:59], 0, v[160:161]
	v_mul_f32_e32 v61, 0x3d372713, v53
	v_mul_f32_e32 v60, v52, v60
	v_mul_f32_e32 v61, v53, v61
	global_store_dwordx2 v[58:59], v[56:57], off sc0 sc1
	v_mul_f32_e32 v58, 0x3d372713, v54
	v_mul_f32_e32 v59, 0x3d372713, v55
	v_fma_f32 v60, v52, v60, v52
	v_fma_f32 v61, v53, v61, v53
	v_mul_f32_e32 v58, v54, v58
	v_mul_f32_e32 v59, v55, v59
	v_mul_f32_e32 v60, 0x3f4c422a, v60
	v_mul_f32_e32 v61, 0x3f4c422a, v61
	v_fma_f32 v58, v54, v58, v54
	v_fma_f32 v59, v55, v59, v55
	v_add_f32_e32 v60, v60, v60
	v_add_f32_e32 v61, v61, v61
	v_mul_f32_e32 v58, 0x3f4c422a, v58
	v_mul_f32_e32 v59, 0x3f4c422a, v59
	v_mul_f32_e32 v60, 0x3fb8aa3b, v60
	v_mul_f32_e32 v61, 0x3fb8aa3b, v61
	v_add_f32_e32 v58, v58, v58
	v_add_f32_e32 v59, v59, v59
	v_exp_f32_e32 v60, v60
	v_exp_f32_e32 v61, v61
	v_mul_f32_e32 v58, 0x3fb8aa3b, v58
	v_mul_f32_e32 v59, 0x3fb8aa3b, v59
	v_exp_f32_e32 v58, v58
	v_exp_f32_e32 v59, v59
	v_add_f32_e32 v56, 1.0, v60
	v_add_f32_e32 v57, 1.0, v61
	v_rcp_f32_e32 v56, v56
	v_rcp_f32_e32 v57, v57
	v_add_f32_e32 v58, 1.0, v58
	v_add_f32_e32 v59, 1.0, v59
	v_rcp_f32_e32 v58, v58
	v_rcp_f32_e32 v59, v59
	v_pk_add_f32 v[56:57], v[56:57], 1.0 op_sel_hi:[1,0] neg_lo:[1,0] neg_hi:[1,0]
	s_nop 0
	v_pk_mul_f32 v[52:53], v[52:53], v[56:57]
	v_pk_add_f32 v[56:57], v[58:59], 1.0 op_sel_hi:[1,0] neg_lo:[1,0] neg_hi:[1,0]
	v_cvt_pk_bf16_f32 v52, v52, v53
	v_pk_mul_f32 v[54:55], v[54:55], v[56:57]
	v_mul_f32_e32 v56, 0x3d372713, v48
	v_cvt_pk_bf16_f32 v53, v54, v55
	v_lshl_add_u64 v[54:55], v[62:63], 0, v[116:117]
	v_lshl_add_u64 v[54:55], v[54:55], 0, s[74:75]
	v_lshl_add_u64 v[54:55], v[54:55], 0, v[160:161]
	v_mul_f32_e32 v57, 0x3d372713, v49
	v_mul_f32_e32 v56, v48, v56
	v_mul_f32_e32 v57, v49, v57
	global_store_dwordx2 v[54:55], v[52:53], off sc0 sc1
	v_mul_f32_e32 v54, 0x3d372713, v50
	v_mul_f32_e32 v55, 0x3d372713, v51
	v_fma_f32 v56, v48, v56, v48
	v_fma_f32 v57, v49, v57, v49
	v_mul_f32_e32 v54, v50, v54
	v_mul_f32_e32 v55, v51, v55
	v_mul_f32_e32 v56, 0x3f4c422a, v56
	v_mul_f32_e32 v57, 0x3f4c422a, v57
	v_fma_f32 v54, v50, v54, v50
	v_fma_f32 v55, v51, v55, v51
	v_add_f32_e32 v56, v56, v56
	v_add_f32_e32 v57, v57, v57
	v_mul_f32_e32 v54, 0x3f4c422a, v54
	v_mul_f32_e32 v55, 0x3f4c422a, v55
; __device__ __forceinline__ unsigned cvt_pk_bf16(float lo, float hi) { const f32x2_t v = {lo, hi}; const bf16x2_t b = __builtin_convertvector(v, bf16x2_t); return __builtin_bit_cast(unsigned, b); }
; __device__ __forceinline__ float gelu_tanh(float y) { const float u = 0.7978845608028654f * (y + 0.044715f * y * y * y); return y * (1.0f - __builtin_amdgcn_rcpf(1.0f + __expf(2.0f * u))); }
;     __device__ __forceinline__ void operator()(const Acc& acc, const Unit& u, int wr, int wc, int fr, int fq) const {
;     ...
;             for (int m = 0; m < 4; ++m) { const int crow = u.pm * 256 + ai * 128 + wr * 64 + m * 16 + fr;
; #pragma unroll
;                 for (int bj = 0; bj < 2; ++bj)
; #pragma unroll
;                     for (int n = 0; n < 2; ++n) { const int col = bj * 128 + wc * 32 + n * 16 + fq * 4, t = col >> 4, cp = col & 15; const f32x4 v = acc[ai][bj][m][n];
;                         *(u32x2*)(Z + ((size_t)crow * 16 + t) * 256 + u.z * 16 + cp) = (u32x2){cvt_pk_bf16(gelu_tanh(v[0]), gelu_tanh(v[1])), cvt_pk_bf16(gelu_tanh(v[2]), gelu_tanh(v[3]))}; } }
	v_mul_f32_e32 v56, 0x3fb8aa3b, v56
	v_mul_f32_e32 v57, 0x3fb8aa3b, v57
	v_add_f32_e32 v54, v54, v54
	v_add_f32_e32 v55, v55, v55
	v_exp_f32_e32 v56, v56
	v_exp_f32_e32 v57, v57
	v_mul_f32_e32 v54, 0x3fb8aa3b, v54
	v_mul_f32_e32 v55, 0x3fb8aa3b, v55
	v_exp_f32_e32 v54, v54
	v_exp_f32_e32 v55, v55
	v_add_f32_e32 v52, 1.0, v56
	v_add_f32_e32 v53, 1.0, v57
	v_rcp_f32_e32 v52, v52
	v_rcp_f32_e32 v53, v53
	v_add_f32_e32 v54, 1.0, v54
	v_add_f32_e32 v55, 1.0, v55
	v_rcp_f32_e32 v54, v54
	v_rcp_f32_e32 v55, v55
	v_pk_add_f32 v[52:53], v[52:53], 1.0 op_sel_hi:[1,0] neg_lo:[1,0] neg_hi:[1,0]
	s_nop 0
	v_pk_mul_f32 v[48:49], v[48:49], v[52:53]
	v_pk_add_f32 v[52:53], v[54:55], 1.0 op_sel_hi:[1,0] neg_lo:[1,0] neg_hi:[1,0]
	v_cvt_pk_bf16_f32 v48, v48, v49
	v_pk_mul_f32 v[50:51], v[50:51], v[52:53]
	v_mul_f32_e32 v52, 0x3d372713, v46
	v_cvt_pk_bf16_f32 v49, v50, v51
	v_lshl_add_u64 v[50:51], v[62:63], 0, v[112:113]
	v_lshl_add_u64 v[50:51], v[50:51], 0, s[74:75]
	v_lshl_add_u64 v[50:51], v[50:51], 0, v[160:161]
	global_store_dwordx2 v[50:51], v[48:49], off sc0 sc1
	v_mul_f32_e32 v50, 0x3d372713, v44
	v_mul_f32_e32 v51, 0x3d372713, v45
	v_mul_f32_e32 v50, v44, v50
	v_mul_f32_e32 v51, v45, v51
	v_mul_f32_e32 v53, 0x3d372713, v47
	v_fma_f32 v50, v44, v50, v44
	v_fma_f32 v51, v45, v51, v45
	v_mul_f32_e32 v52, v46, v52
	v_mul_f32_e32 v53, v47, v53
	v_mul_f32_e32 v50, 0x3f4c422a, v50
	v_mul_f32_e32 v51, 0x3f4c422a, v51
	v_fma_f32 v52, v46, v52, v46
	v_fma_f32 v53, v47, v53, v47
	v_add_f32_e32 v50, v50, v50
	v_add_f32_e32 v51, v51, v51
	v_mul_f32_e32 v52, 0x3f4c422a, v52
	v_mul_f32_e32 v53, 0x3f4c422a, v53
	v_mul_f32_e32 v50, 0x3fb8aa3b, v50
	v_mul_f32_e32 v51, 0x3fb8aa3b, v51
	v_add_f32_e32 v52, v52, v52
	v_add_f32_e32 v53, v53, v53
	v_exp_f32_e32 v50, v50
	v_exp_f32_e32 v51, v51
	v_mul_f32_e32 v52, 0x3fb8aa3b, v52
	v_mul_f32_e32 v53, 0x3fb8aa3b, v53
	v_exp_f32_e32 v52, v52
	v_exp_f32_e32 v53, v53
	v_add_f32_e32 v50, 1.0, v50
	v_add_f32_e32 v51, 1.0, v51
	v_rcp_f32_e32 v50, v50
	v_rcp_f32_e32 v51, v51
	v_add_f32_e32 v52, 1.0, v52
	v_add_f32_e32 v53, 1.0, v53
	v_rcp_f32_e32 v52, v52
	v_rcp_f32_e32 v53, v53
	v_add_u32_e32 v48, 0x90, v128
	v_pk_add_f32 v[50:51], v[50:51], 1.0 op_sel_hi:[1,0] neg_lo:[1,0] neg_hi:[1,0]
	v_ashrrev_i32_e32 v49, 31, v48
	v_pk_mul_f32 v[44:45], v[44:45], v[50:51]
	v_pk_add_f32 v[50:51], v[52:53], 1.0 op_sel_hi:[1,0] neg_lo:[1,0] neg_hi:[1,0]
	v_lshlrev_b64 v[48:49], 13, v[48:49]
	v_pk_mul_f32 v[46:47], v[46:47], v[50:51]
	v_cvt_pk_bf16_f32 v44, v44, v45
	v_cvt_pk_bf16_f32 v45, v46, v47
	v_lshl_add_u64 v[46:47], s[0:1], 0, v[48:49]
	v_lshl_add_u64 v[48:49], v[46:47], 0, v[124:125]
	v_lshl_add_u64 v[48:49], v[48:49], 0, s[74:75]
	v_lshl_add_u64 v[48:49], v[48:49], 0, v[160:161]
	v_mul_f32_e32 v50, 0x3d372713, v40
	v_mul_f32_e32 v51, 0x3d372713, v41
	v_mul_f32_e32 v50, v40, v50
	v_mul_f32_e32 v51, v41, v51
	global_store_dwordx2 v[48:49], v[44:45], off sc0 sc1
	v_mul_f32_e32 v48, 0x3d372713, v42
	v_mul_f32_e32 v49, 0x3d372713, v43
	v_fma_f32 v50, v40, v50, v40
	v_fma_f32 v51, v41, v51, v41
	v_mul_f32_e32 v48, v42, v48
	v_mul_f32_e32 v49, v43, v49
	v_mul_f32_e32 v50, 0x3f4c422a, v50
	v_mul_f32_e32 v51, 0x3f4c422a, v51
	v_fma_f32 v48, v42, v48, v42
	v_fma_f32 v49, v43, v49, v43
	v_add_f32_e32 v50, v50, v50
	v_add_f32_e32 v51, v51, v51
	v_mul_f32_e32 v48, 0x3f4c422a, v48
	v_mul_f32_e32 v49, 0x3f4c422a, v49
	v_mul_f32_e32 v50, 0x3fb8aa3b, v50
	v_mul_f32_e32 v51, 0x3fb8aa3b, v51
	v_add_f32_e32 v48, v48, v48
	v_add_f32_e32 v49, v49, v49
	v_exp_f32_e32 v50, v50
	v_exp_f32_e32 v51, v51
	v_mul_f32_e32 v48, 0x3fb8aa3b, v48
	v_mul_f32_e32 v49, 0x3fb8aa3b, v49
	v_exp_f32_e32 v48, v48
	v_exp_f32_e32 v49, v49
	v_add_f32_e32 v44, 1.0, v50
	v_add_f32_e32 v45, 1.0, v51
	v_rcp_f32_e32 v44, v44
	v_rcp_f32_e32 v45, v45
	v_add_f32_e32 v48, 1.0, v48
	v_add_f32_e32 v49, 1.0, v49
	v_rcp_f32_e32 v48, v48
	v_rcp_f32_e32 v49, v49
	v_pk_add_f32 v[44:45], v[44:45], 1.0 op_sel_hi:[1,0] neg_lo:[1,0] neg_hi:[1,0]
	s_nop 0
	v_pk_mul_f32 v[40:41], v[40:41], v[44:45]
	v_pk_add_f32 v[44:45], v[48:49], 1.0 op_sel_hi:[1,0] neg_lo:[1,0] neg_hi:[1,0]
	v_cvt_pk_bf16_f32 v40, v40, v41
	v_pk_mul_f32 v[42:43], v[42:43], v[44:45]
	v_mul_f32_e32 v44, 0x3d372713, v36
	v_cvt_pk_bf16_f32 v41, v42, v43
	v_lshl_add_u64 v[42:43], v[46:47], 0, v[120:121]
	v_lshl_add_u64 v[42:43], v[42:43], 0, s[74:75]
	v_lshl_add_u64 v[42:43], v[42:43], 0, v[160:161]
	v_mul_f32_e32 v45, 0x3d372713, v37
	v_mul_f32_e32 v44, v36, v44
	v_mul_f32_e32 v45, v37, v45
	global_store_dwordx2 v[42:43], v[40:41], off sc0 sc1
	v_mul_f32_e32 v42, 0x3d372713, v38
	v_mul_f32_e32 v43, 0x3d372713, v39
	v_fma_f32 v44, v36, v44, v36
	v_fma_f32 v45, v37, v45, v37
	v_mul_f32_e32 v42, v38, v42
	v_mul_f32_e32 v43, v39, v43
	v_mul_f32_e32 v44, 0x3f4c422a, v44
	v_mul_f32_e32 v45, 0x3f4c422a, v45
	v_fma_f32 v42, v38, v42, v38
	v_fma_f32 v43, v39, v43, v39
	v_add_f32_e32 v44, v44, v44
	v_add_f32_e32 v45, v45, v45
	v_mul_f32_e32 v42, 0x3f4c422a, v42
	v_mul_f32_e32 v43, 0x3f4c422a, v43
	v_mul_f32_e32 v44, 0x3fb8aa3b, v44
	v_mul_f32_e32 v45, 0x3fb8aa3b, v45
	v_add_f32_e32 v42, v42, v42
	v_add_f32_e32 v43, v43, v43
	v_exp_f32_e32 v44, v44
	v_exp_f32_e32 v45, v45
	v_mul_f32_e32 v42, 0x3fb8aa3b, v42
	v_mul_f32_e32 v43, 0x3fb8aa3b, v43
	v_exp_f32_e32 v42, v42
	v_exp_f32_e32 v43, v43
	v_add_f32_e32 v40, 1.0, v44
	v_add_f32_e32 v41, 1.0, v45
	v_rcp_f32_e32 v40, v40
	v_rcp_f32_e32 v41, v41
	v_add_f32_e32 v42, 1.0, v42
	v_add_f32_e32 v43, 1.0, v43
	v_rcp_f32_e32 v42, v42
	v_rcp_f32_e32 v43, v43
	v_pk_add_f32 v[40:41], v[40:41], 1.0 op_sel_hi:[1,0] neg_lo:[1,0] neg_hi:[1,0]
	s_nop 0
	v_pk_mul_f32 v[36:37], v[36:37], v[40:41]
; __device__ __forceinline__ unsigned cvt_pk_bf16(float lo, float hi) { const f32x2_t v = {lo, hi}; const bf16x2_t b = __builtin_convertvector(v, bf16x2_t); return __builtin_bit_cast(unsigned, b); }
; __device__ __forceinline__ float gelu_tanh(float y) { const float u = 0.7978845608028654f * (y + 0.044715f * y * y * y); return y * (1.0f - __builtin_amdgcn_rcpf(1.0f + __expf(2.0f * u))); }
;     __device__ __forceinline__ void operator()(const Acc& acc, const Unit& u, int wr, int wc, int fr, int fq) const {
;     ...
;             for (int m = 0; m < 4; ++m) { const int crow = u.pm * 256 + ai * 128 + wr * 64 + m * 16 + fr;
; #pragma unroll
;                 for (int bj = 0; bj < 2; ++bj)
; #pragma unroll
;                     for (int n = 0; n < 2; ++n) { const int col = bj * 128 + wc * 32 + n * 16 + fq * 4, t = col >> 4, cp = col & 15; const f32x4 v = acc[ai][bj][m][n];
;                         *(u32x2*)(Z + ((size_t)crow * 16 + t) * 256 + u.z * 16 + cp) = (u32x2){cvt_pk_bf16(gelu_tanh(v[0]), gelu_tanh(v[1])), cvt_pk_bf16(gelu_tanh(v[2]), gelu_tanh(v[3]))}; } }
	v_pk_add_f32 v[40:41], v[42:43], 1.0 op_sel_hi:[1,0] neg_lo:[1,0] neg_hi:[1,0]
	v_cvt_pk_bf16_f32 v36, v36, v37
	v_pk_mul_f32 v[38:39], v[38:39], v[40:41]
	v_mul_f32_e32 v40, 0x3d372713, v32
	v_cvt_pk_bf16_f32 v37, v38, v39
	v_lshl_add_u64 v[38:39], v[46:47], 0, v[116:117]
	v_lshl_add_u64 v[38:39], v[38:39], 0, s[74:75]
	v_lshl_add_u64 v[38:39], v[38:39], 0, v[160:161]
	v_mul_f32_e32 v41, 0x3d372713, v33
	v_mul_f32_e32 v40, v32, v40
	v_mul_f32_e32 v41, v33, v41
	global_store_dwordx2 v[38:39], v[36:37], off sc0 sc1
	v_mul_f32_e32 v38, 0x3d372713, v34
	v_mul_f32_e32 v39, 0x3d372713, v35
	v_fma_f32 v40, v32, v40, v32
	v_fma_f32 v41, v33, v41, v33
	v_mul_f32_e32 v38, v34, v38
	v_mul_f32_e32 v39, v35, v39
	v_mul_f32_e32 v40, 0x3f4c422a, v40
	v_mul_f32_e32 v41, 0x3f4c422a, v41
	v_fma_f32 v38, v34, v38, v34
	v_fma_f32 v39, v35, v39, v35
	v_add_f32_e32 v40, v40, v40
	v_add_f32_e32 v41, v41, v41
	v_mul_f32_e32 v38, 0x3f4c422a, v38
	v_mul_f32_e32 v39, 0x3f4c422a, v39
	v_mul_f32_e32 v40, 0x3fb8aa3b, v40
	v_mul_f32_e32 v41, 0x3fb8aa3b, v41
	v_add_f32_e32 v38, v38, v38
	v_add_f32_e32 v39, v39, v39
	v_exp_f32_e32 v40, v40
	v_exp_f32_e32 v41, v41
	v_mul_f32_e32 v38, 0x3fb8aa3b, v38
	v_mul_f32_e32 v39, 0x3fb8aa3b, v39
	v_exp_f32_e32 v38, v38
	v_exp_f32_e32 v39, v39
	v_add_f32_e32 v36, 1.0, v40
	v_add_f32_e32 v37, 1.0, v41
	v_rcp_f32_e32 v36, v36
	v_rcp_f32_e32 v37, v37
	v_add_f32_e32 v38, 1.0, v38
	v_add_f32_e32 v39, 1.0, v39
	v_rcp_f32_e32 v38, v38
	v_rcp_f32_e32 v39, v39
	v_pk_add_f32 v[36:37], v[36:37], 1.0 op_sel_hi:[1,0] neg_lo:[1,0] neg_hi:[1,0]
	s_nop 0
	v_pk_mul_f32 v[32:33], v[32:33], v[36:37]
	v_pk_add_f32 v[36:37], v[38:39], 1.0 op_sel_hi:[1,0] neg_lo:[1,0] neg_hi:[1,0]
	v_cvt_pk_bf16_f32 v32, v32, v33
	v_pk_mul_f32 v[34:35], v[34:35], v[36:37]
	v_mul_f32_e32 v36, 0x3d372713, v30
	v_cvt_pk_bf16_f32 v33, v34, v35
	v_lshl_add_u64 v[34:35], v[46:47], 0, v[112:113]
	v_lshl_add_u64 v[34:35], v[34:35], 0, s[74:75]
	v_lshl_add_u64 v[34:35], v[34:35], 0, v[160:161]
	global_store_dwordx2 v[34:35], v[32:33], off sc0 sc1
	v_mul_f32_e32 v34, 0x3d372713, v28
	v_mul_f32_e32 v35, 0x3d372713, v29
	v_mul_f32_e32 v34, v28, v34
	v_mul_f32_e32 v35, v29, v35
	v_mul_f32_e32 v37, 0x3d372713, v31
	v_fma_f32 v34, v28, v34, v28
	v_fma_f32 v35, v29, v35, v29
	v_mul_f32_e32 v36, v30, v36
	v_mul_f32_e32 v37, v31, v37
	v_mul_f32_e32 v34, 0x3f4c422a, v34
	v_mul_f32_e32 v35, 0x3f4c422a, v35
	v_fma_f32 v36, v30, v36, v30
	v_fma_f32 v37, v31, v37, v31
	v_add_f32_e32 v34, v34, v34
	v_add_f32_e32 v35, v35, v35
	v_mul_f32_e32 v36, 0x3f4c422a, v36
	v_mul_f32_e32 v37, 0x3f4c422a, v37
	v_mul_f32_e32 v34, 0x3fb8aa3b, v34
	v_mul_f32_e32 v35, 0x3fb8aa3b, v35
	v_add_f32_e32 v36, v36, v36
	v_add_f32_e32 v37, v37, v37
	v_exp_f32_e32 v34, v34
	v_exp_f32_e32 v35, v35
	v_mul_f32_e32 v36, 0x3fb8aa3b, v36
	v_mul_f32_e32 v37, 0x3fb8aa3b, v37
	v_exp_f32_e32 v36, v36
	v_exp_f32_e32 v37, v37
	v_add_f32_e32 v34, 1.0, v34
	v_add_f32_e32 v35, 1.0, v35
	v_rcp_f32_e32 v34, v34
	v_rcp_f32_e32 v35, v35
	v_add_f32_e32 v36, 1.0, v36
	v_add_f32_e32 v37, 1.0, v37
	v_rcp_f32_e32 v36, v36
	v_rcp_f32_e32 v37, v37
	v_add_u32_e32 v32, 0xa0, v128
	v_pk_add_f32 v[34:35], v[34:35], 1.0 op_sel_hi:[1,0] neg_lo:[1,0] neg_hi:[1,0]
	v_ashrrev_i32_e32 v33, 31, v32
	v_pk_mul_f32 v[28:29], v[28:29], v[34:35]
	v_pk_add_f32 v[34:35], v[36:37], 1.0 op_sel_hi:[1,0] neg_lo:[1,0] neg_hi:[1,0]
	v_lshlrev_b64 v[32:33], 13, v[32:33]
	v_pk_mul_f32 v[30:31], v[30:31], v[34:35]
	v_cvt_pk_bf16_f32 v28, v28, v29
	v_cvt_pk_bf16_f32 v29, v30, v31
	v_lshl_add_u64 v[30:31], s[0:1], 0, v[32:33]
	v_lshl_add_u64 v[32:33], v[30:31], 0, v[124:125]
	v_lshl_add_u64 v[32:33], v[32:33], 0, s[74:75]
	v_lshl_add_u64 v[32:33], v[32:33], 0, v[160:161]
	v_mul_f32_e32 v34, 0x3d372713, v24
	v_mul_f32_e32 v35, 0x3d372713, v25
	v_mul_f32_e32 v34, v24, v34
	v_mul_f32_e32 v35, v25, v35
	global_store_dwordx2 v[32:33], v[28:29], off sc0 sc1
	v_mul_f32_e32 v32, 0x3d372713, v26
	v_mul_f32_e32 v33, 0x3d372713, v27
	v_fma_f32 v34, v24, v34, v24
	v_fma_f32 v35, v25, v35, v25
	v_mul_f32_e32 v32, v26, v32
	v_mul_f32_e32 v33, v27, v33
	v_mul_f32_e32 v34, 0x3f4c422a, v34
	v_mul_f32_e32 v35, 0x3f4c422a, v35
	v_fma_f32 v32, v26, v32, v26
	v_fma_f32 v33, v27, v33, v27
	v_add_f32_e32 v34, v34, v34
	v_add_f32_e32 v35, v35, v35
	v_mul_f32_e32 v32, 0x3f4c422a, v32
	v_mul_f32_e32 v33, 0x3f4c422a, v33
	v_mul_f32_e32 v34, 0x3fb8aa3b, v34
	v_mul_f32_e32 v35, 0x3fb8aa3b, v35
	v_add_f32_e32 v32, v32, v32
	v_add_f32_e32 v33, v33, v33
	v_exp_f32_e32 v34, v34
	v_exp_f32_e32 v35, v35
	v_mul_f32_e32 v32, 0x3fb8aa3b, v32
	v_mul_f32_e32 v33, 0x3fb8aa3b, v33
	v_exp_f32_e32 v32, v32
	v_exp_f32_e32 v33, v33
	v_add_f32_e32 v28, 1.0, v34
	v_add_f32_e32 v29, 1.0, v35
	v_rcp_f32_e32 v28, v28
	v_rcp_f32_e32 v29, v29
	v_add_f32_e32 v32, 1.0, v32
	v_add_f32_e32 v33, 1.0, v33
	v_rcp_f32_e32 v32, v32
	v_rcp_f32_e32 v33, v33
	v_pk_add_f32 v[28:29], v[28:29], 1.0 op_sel_hi:[1,0] neg_lo:[1,0] neg_hi:[1,0]
	s_nop 0
	v_pk_mul_f32 v[24:25], v[24:25], v[28:29]
	v_pk_add_f32 v[28:29], v[32:33], 1.0 op_sel_hi:[1,0] neg_lo:[1,0] neg_hi:[1,0]
	v_cvt_pk_bf16_f32 v24, v24, v25
	v_pk_mul_f32 v[26:27], v[26:27], v[28:29]
	v_mul_f32_e32 v28, 0x3d372713, v20
	v_cvt_pk_bf16_f32 v25, v26, v27
	v_lshl_add_u64 v[26:27], v[30:31], 0, v[120:121]
	v_lshl_add_u64 v[26:27], v[26:27], 0, s[74:75]
	v_lshl_add_u64 v[26:27], v[26:27], 0, v[160:161]
	v_mul_f32_e32 v29, 0x3d372713, v21
	v_mul_f32_e32 v28, v20, v28
	v_mul_f32_e32 v29, v21, v29
	global_store_dwordx2 v[26:27], v[24:25], off sc0 sc1
	v_mul_f32_e32 v26, 0x3d372713, v22
	v_mul_f32_e32 v27, 0x3d372713, v23
	v_fma_f32 v28, v20, v28, v20
	v_fma_f32 v29, v21, v29, v21
; __device__ __forceinline__ unsigned cvt_pk_bf16(float lo, float hi) { const f32x2_t v = {lo, hi}; const bf16x2_t b = __builtin_convertvector(v, bf16x2_t); return __builtin_bit_cast(unsigned, b); }
; __device__ __forceinline__ float gelu_tanh(float y) { const float u = 0.7978845608028654f * (y + 0.044715f * y * y * y); return y * (1.0f - __builtin_amdgcn_rcpf(1.0f + __expf(2.0f * u))); }
;     __device__ __forceinline__ void operator()(const Acc& acc, const Unit& u, int wr, int wc, int fr, int fq) const {
;     ...
;             for (int m = 0; m < 4; ++m) { const int crow = u.pm * 256 + ai * 128 + wr * 64 + m * 16 + fr;
; #pragma unroll
;                 for (int bj = 0; bj < 2; ++bj)
; #pragma unroll
;                     for (int n = 0; n < 2; ++n) { const int col = bj * 128 + wc * 32 + n * 16 + fq * 4, t = col >> 4, cp = col & 15; const f32x4 v = acc[ai][bj][m][n];
;                         *(u32x2*)(Z + ((size_t)crow * 16 + t) * 256 + u.z * 16 + cp) = (u32x2){cvt_pk_bf16(gelu_tanh(v[0]), gelu_tanh(v[1])), cvt_pk_bf16(gelu_tanh(v[2]), gelu_tanh(v[3]))}; } }
	v_mul_f32_e32 v26, v22, v26
	v_mul_f32_e32 v27, v23, v27
	v_mul_f32_e32 v28, 0x3f4c422a, v28
	v_mul_f32_e32 v29, 0x3f4c422a, v29
	v_fma_f32 v26, v22, v26, v22
	v_fma_f32 v27, v23, v27, v23
	v_add_f32_e32 v28, v28, v28
	v_add_f32_e32 v29, v29, v29
	v_mul_f32_e32 v26, 0x3f4c422a, v26
	v_mul_f32_e32 v27, 0x3f4c422a, v27
	v_mul_f32_e32 v28, 0x3fb8aa3b, v28
	v_mul_f32_e32 v29, 0x3fb8aa3b, v29
	v_add_f32_e32 v26, v26, v26
	v_add_f32_e32 v27, v27, v27
	v_exp_f32_e32 v28, v28
	v_exp_f32_e32 v29, v29
	v_mul_f32_e32 v26, 0x3fb8aa3b, v26
	v_mul_f32_e32 v27, 0x3fb8aa3b, v27
	v_exp_f32_e32 v26, v26
	v_exp_f32_e32 v27, v27
	v_add_f32_e32 v24, 1.0, v28
	v_add_f32_e32 v25, 1.0, v29
	v_rcp_f32_e32 v24, v24
	v_rcp_f32_e32 v25, v25
	v_add_f32_e32 v26, 1.0, v26
	v_add_f32_e32 v27, 1.0, v27
	v_rcp_f32_e32 v26, v26
	v_rcp_f32_e32 v27, v27
	v_pk_add_f32 v[24:25], v[24:25], 1.0 op_sel_hi:[1,0] neg_lo:[1,0] neg_hi:[1,0]
	s_nop 0
	v_pk_mul_f32 v[20:21], v[20:21], v[24:25]
	v_pk_add_f32 v[24:25], v[26:27], 1.0 op_sel_hi:[1,0] neg_lo:[1,0] neg_hi:[1,0]
	v_cvt_pk_bf16_f32 v20, v20, v21
	v_pk_mul_f32 v[22:23], v[22:23], v[24:25]
	v_mul_f32_e32 v24, 0x3d372713, v16
	v_cvt_pk_bf16_f32 v21, v22, v23
	v_lshl_add_u64 v[22:23], v[30:31], 0, v[116:117]
	v_lshl_add_u64 v[22:23], v[22:23], 0, s[74:75]
	v_lshl_add_u64 v[22:23], v[22:23], 0, v[160:161]
	v_mul_f32_e32 v25, 0x3d372713, v17
	v_mul_f32_e32 v24, v16, v24
	v_mul_f32_e32 v25, v17, v25
	global_store_dwordx2 v[22:23], v[20:21], off sc0 sc1
	v_mul_f32_e32 v22, 0x3d372713, v18
	v_mul_f32_e32 v23, 0x3d372713, v19
	v_fma_f32 v24, v16, v24, v16
	v_fma_f32 v25, v17, v25, v17
	v_mul_f32_e32 v22, v18, v22
	v_mul_f32_e32 v23, v19, v23
	v_mul_f32_e32 v24, 0x3f4c422a, v24
	v_mul_f32_e32 v25, 0x3f4c422a, v25
	v_fma_f32 v22, v18, v22, v18
	v_fma_f32 v23, v19, v23, v19
	v_add_f32_e32 v24, v24, v24
	v_add_f32_e32 v25, v25, v25
	v_mul_f32_e32 v22, 0x3f4c422a, v22
	v_mul_f32_e32 v23, 0x3f4c422a, v23
	v_mul_f32_e32 v24, 0x3fb8aa3b, v24
	v_mul_f32_e32 v25, 0x3fb8aa3b, v25
	v_add_f32_e32 v22, v22, v22
	v_add_f32_e32 v23, v23, v23
	v_exp_f32_e32 v24, v24
	v_exp_f32_e32 v25, v25
	v_mul_f32_e32 v22, 0x3fb8aa3b, v22
	v_mul_f32_e32 v23, 0x3fb8aa3b, v23
	v_exp_f32_e32 v22, v22
	v_exp_f32_e32 v23, v23
	v_add_f32_e32 v20, 1.0, v24
	v_add_f32_e32 v21, 1.0, v25
	v_rcp_f32_e32 v20, v20
	v_rcp_f32_e32 v21, v21
	v_add_f32_e32 v22, 1.0, v22
	v_add_f32_e32 v23, 1.0, v23
	v_rcp_f32_e32 v22, v22
	v_rcp_f32_e32 v23, v23
	v_pk_add_f32 v[20:21], v[20:21], 1.0 op_sel_hi:[1,0] neg_lo:[1,0] neg_hi:[1,0]
	s_nop 0
	v_pk_mul_f32 v[16:17], v[16:17], v[20:21]
	v_pk_add_f32 v[20:21], v[22:23], 1.0 op_sel_hi:[1,0] neg_lo:[1,0] neg_hi:[1,0]
	v_cvt_pk_bf16_f32 v16, v16, v17
	v_pk_mul_f32 v[18:19], v[18:19], v[20:21]
	v_mul_f32_e32 v20, 0x3d372713, v14
	v_cvt_pk_bf16_f32 v17, v18, v19
	v_lshl_add_u64 v[18:19], v[30:31], 0, v[112:113]
	v_lshl_add_u64 v[18:19], v[18:19], 0, s[74:75]
	v_lshl_add_u64 v[18:19], v[18:19], 0, v[160:161]
	global_store_dwordx2 v[18:19], v[16:17], off sc0 sc1
	v_mul_f32_e32 v18, 0x3d372713, v12
	v_mul_f32_e32 v19, 0x3d372713, v13
	v_mul_f32_e32 v18, v12, v18
	v_mul_f32_e32 v19, v13, v19
	v_mul_f32_e32 v21, 0x3d372713, v15
	v_fma_f32 v18, v12, v18, v12
	v_fma_f32 v19, v13, v19, v13
	v_mul_f32_e32 v20, v14, v20
	v_mul_f32_e32 v21, v15, v21
	v_mul_f32_e32 v18, 0x3f4c422a, v18
	v_mul_f32_e32 v19, 0x3f4c422a, v19
	v_fma_f32 v20, v14, v20, v14
	v_fma_f32 v21, v15, v21, v15
	v_add_f32_e32 v18, v18, v18
	v_add_f32_e32 v19, v19, v19
	v_mul_f32_e32 v20, 0x3f4c422a, v20
	v_mul_f32_e32 v21, 0x3f4c422a, v21
	v_mul_f32_e32 v18, 0x3fb8aa3b, v18
	v_mul_f32_e32 v19, 0x3fb8aa3b, v19
	v_add_f32_e32 v20, v20, v20
	v_add_f32_e32 v21, v21, v21
	v_exp_f32_e32 v18, v18
	v_exp_f32_e32 v19, v19
	v_mul_f32_e32 v20, 0x3fb8aa3b, v20
	v_mul_f32_e32 v21, 0x3fb8aa3b, v21
	v_exp_f32_e32 v20, v20
	v_exp_f32_e32 v21, v21
	v_add_f32_e32 v18, 1.0, v18
	v_add_f32_e32 v19, 1.0, v19
	v_rcp_f32_e32 v18, v18
	v_rcp_f32_e32 v19, v19
	v_add_f32_e32 v20, 1.0, v20
	v_add_f32_e32 v21, 1.0, v21
	v_rcp_f32_e32 v20, v20
	v_rcp_f32_e32 v21, v21
	v_add_u32_e32 v16, 0xb0, v128
	v_pk_add_f32 v[18:19], v[18:19], 1.0 op_sel_hi:[1,0] neg_lo:[1,0] neg_hi:[1,0]
	v_ashrrev_i32_e32 v17, 31, v16
	v_pk_mul_f32 v[12:13], v[12:13], v[18:19]
	v_pk_add_f32 v[18:19], v[20:21], 1.0 op_sel_hi:[1,0] neg_lo:[1,0] neg_hi:[1,0]
	v_lshlrev_b64 v[16:17], 13, v[16:17]
	v_pk_mul_f32 v[14:15], v[14:15], v[18:19]
	v_cvt_pk_bf16_f32 v12, v12, v13
	v_cvt_pk_bf16_f32 v13, v14, v15
	v_lshl_add_u64 v[14:15], s[0:1], 0, v[16:17]
	v_lshl_add_u64 v[16:17], v[14:15], 0, v[124:125]
	v_lshl_add_u64 v[16:17], v[16:17], 0, s[74:75]
	v_lshl_add_u64 v[16:17], v[16:17], 0, v[160:161]
	v_mul_f32_e32 v18, 0x3d372713, v8
	v_mul_f32_e32 v19, 0x3d372713, v9
	v_mul_f32_e32 v18, v8, v18
	v_mul_f32_e32 v19, v9, v19
	global_store_dwordx2 v[16:17], v[12:13], off sc0 sc1
	v_mul_f32_e32 v16, 0x3d372713, v10
	v_mul_f32_e32 v17, 0x3d372713, v11
	v_fma_f32 v18, v8, v18, v8
	v_fma_f32 v19, v9, v19, v9
	v_mul_f32_e32 v16, v10, v16
	v_mul_f32_e32 v17, v11, v17
	v_mul_f32_e32 v18, 0x3f4c422a, v18
	v_mul_f32_e32 v19, 0x3f4c422a, v19
	v_fma_f32 v16, v10, v16, v10
	v_fma_f32 v17, v11, v17, v11
	v_add_f32_e32 v18, v18, v18
	v_add_f32_e32 v19, v19, v19
	v_mul_f32_e32 v16, 0x3f4c422a, v16
	v_mul_f32_e32 v17, 0x3f4c422a, v17
	v_mul_f32_e32 v18, 0x3fb8aa3b, v18
; __device__ __forceinline__ unsigned cvt_pk_bf16(float lo, float hi) { const f32x2_t v = {lo, hi}; const bf16x2_t b = __builtin_convertvector(v, bf16x2_t); return __builtin_bit_cast(unsigned, b); }
; __device__ __forceinline__ float gelu_tanh(float y) { const float u = 0.7978845608028654f * (y + 0.044715f * y * y * y); return y * (1.0f - __builtin_amdgcn_rcpf(1.0f + __expf(2.0f * u))); }
; #define INP(i) ((const float*)ld_ptr(pb, (i)))
; #define PHASE_END if (ph + 1 < hi) grid_barrier((unsigned*)ws, (unsigned)G, tid, (volatile LAS unsigned*)(ldsl + XBST_OFF)); } ++ph;
;     __device__ __forceinline__ void operator()(const Acc& acc, const Unit& u, int wr, int wc, int fr, int fq) const {
;     ...
;             for (int m = 0; m < 4; ++m) { const int crow = u.pm * 256 + ai * 128 + wr * 64 + m * 16 + fr;
; #pragma unroll
;                 for (int bj = 0; bj < 2; ++bj)
; #pragma unroll
;                     for (int n = 0; n < 2; ++n) { const int col = bj * 128 + wc * 32 + n * 16 + fq * 4, t = col >> 4, cp = col & 15; const f32x4 v = acc[ai][bj][m][n];
;                         *(u32x2*)(Z + ((size_t)crow * 16 + t) * 256 + u.z * 16 + cp) = (u32x2){cvt_pk_bf16(gelu_tanh(v[0]), gelu_tanh(v[1])), cvt_pk_bf16(gelu_tanh(v[2]), gelu_tanh(v[3]))}; } }
; __global__ void __launch_bounds__(512, 2) hybrid_fwd(Params P) {
;     ...
;             if (bid < 64) {
;                 pg8::Gemm g{ZUT, BTY + (size_t)l * 16 * 256 * KY, KY, KY, KY, (size_t)NCHUNK * KY * 2, (size_t)256 * KY * 2}; pg8::Order S; S.init(4, 1, 16, 64, bid, KY / 64);
;                 EpiY E{Zb};
;                 pg8::gemm_phase<EpiY, true>(ldsl, g, S, E, wave);
;             } else {
;                 const float* sinks = INP(14) + l * 8;
;                 for (int i = bid - 64; i < 128; i += G - 64) { const int task = 256 + i; MIX_TASK(task); }
;                 __syncthreads();
;             }
;         }
;         PHASE_END
	v_mul_f32_e32 v19, 0x3fb8aa3b, v19
	v_add_f32_e32 v16, v16, v16
	v_add_f32_e32 v17, v17, v17
	v_exp_f32_e32 v18, v18
	v_exp_f32_e32 v19, v19
	v_mul_f32_e32 v16, 0x3fb8aa3b, v16
	v_mul_f32_e32 v17, 0x3fb8aa3b, v17
	v_exp_f32_e32 v16, v16
	v_exp_f32_e32 v17, v17
	v_add_f32_e32 v12, 1.0, v18
	v_add_f32_e32 v13, 1.0, v19
	v_rcp_f32_e32 v12, v12
	v_rcp_f32_e32 v13, v13
	v_add_f32_e32 v16, 1.0, v16
	v_add_f32_e32 v17, 1.0, v17
	v_rcp_f32_e32 v16, v16
	v_rcp_f32_e32 v17, v17
	v_pk_add_f32 v[12:13], v[12:13], 1.0 op_sel_hi:[1,0] neg_lo:[1,0] neg_hi:[1,0]
	s_nop 0
	v_pk_mul_f32 v[8:9], v[8:9], v[12:13]
	v_pk_add_f32 v[12:13], v[16:17], 1.0 op_sel_hi:[1,0] neg_lo:[1,0] neg_hi:[1,0]
	v_cvt_pk_bf16_f32 v8, v8, v9
	v_pk_mul_f32 v[10:11], v[10:11], v[12:13]
	v_mul_f32_e32 v12, 0x3d372713, v4
	v_cvt_pk_bf16_f32 v9, v10, v11
	v_lshl_add_u64 v[10:11], v[14:15], 0, v[120:121]
	v_lshl_add_u64 v[10:11], v[10:11], 0, s[74:75]
	v_lshl_add_u64 v[10:11], v[10:11], 0, v[160:161]
	v_mul_f32_e32 v13, 0x3d372713, v5
	v_mul_f32_e32 v12, v4, v12
	v_mul_f32_e32 v13, v5, v13
	global_store_dwordx2 v[10:11], v[8:9], off sc0 sc1
	v_mul_f32_e32 v10, 0x3d372713, v6
	v_mul_f32_e32 v11, 0x3d372713, v7
	v_fma_f32 v12, v4, v12, v4
	v_fma_f32 v13, v5, v13, v5
	v_mul_f32_e32 v10, v6, v10
	v_mul_f32_e32 v11, v7, v11
	v_mul_f32_e32 v12, 0x3f4c422a, v12
	v_mul_f32_e32 v13, 0x3f4c422a, v13
	v_fma_f32 v10, v6, v10, v6
	v_fma_f32 v11, v7, v11, v7
	v_add_f32_e32 v12, v12, v12
	v_add_f32_e32 v13, v13, v13
	v_mul_f32_e32 v10, 0x3f4c422a, v10
	v_mul_f32_e32 v11, 0x3f4c422a, v11
	v_mul_f32_e32 v12, 0x3fb8aa3b, v12
	v_mul_f32_e32 v13, 0x3fb8aa3b, v13
	v_add_f32_e32 v10, v10, v10
	v_add_f32_e32 v11, v11, v11
	v_exp_f32_e32 v12, v12
	v_exp_f32_e32 v13, v13
	v_mul_f32_e32 v10, 0x3fb8aa3b, v10
	v_mul_f32_e32 v11, 0x3fb8aa3b, v11
	v_exp_f32_e32 v10, v10
	v_exp_f32_e32 v11, v11
	v_add_f32_e32 v8, 1.0, v12
	v_add_f32_e32 v9, 1.0, v13
	v_rcp_f32_e32 v8, v8
	v_rcp_f32_e32 v9, v9
	v_add_f32_e32 v10, 1.0, v10
	v_add_f32_e32 v11, 1.0, v11
	v_rcp_f32_e32 v10, v10
	v_rcp_f32_e32 v11, v11
	v_pk_add_f32 v[8:9], v[8:9], 1.0 op_sel_hi:[1,0] neg_lo:[1,0] neg_hi:[1,0]
	s_nop 0
	v_pk_mul_f32 v[4:5], v[4:5], v[8:9]
	v_pk_add_f32 v[8:9], v[10:11], 1.0 op_sel_hi:[1,0] neg_lo:[1,0] neg_hi:[1,0]
	v_cvt_pk_bf16_f32 v4, v4, v5
	v_pk_mul_f32 v[6:7], v[6:7], v[8:9]
	v_mul_f32_e32 v8, 0x3d372713, v0
	v_cvt_pk_bf16_f32 v5, v6, v7
	v_lshl_add_u64 v[6:7], v[14:15], 0, v[116:117]
	v_lshl_add_u64 v[6:7], v[6:7], 0, s[74:75]
	v_lshl_add_u64 v[6:7], v[6:7], 0, v[160:161]
	v_mul_f32_e32 v9, 0x3d372713, v1
	v_mul_f32_e32 v8, v0, v8
	v_mul_f32_e32 v9, v1, v9
	global_store_dwordx2 v[6:7], v[4:5], off sc0 sc1
	v_mul_f32_e32 v6, 0x3d372713, v2
	v_mul_f32_e32 v7, 0x3d372713, v3
	v_fma_f32 v8, v0, v8, v0
	v_fma_f32 v9, v1, v9, v1
	v_mul_f32_e32 v6, v2, v6
	v_mul_f32_e32 v7, v3, v7
	v_mul_f32_e32 v8, 0x3f4c422a, v8
	v_mul_f32_e32 v9, 0x3f4c422a, v9
	v_fma_f32 v6, v2, v6, v2
	v_fma_f32 v7, v3, v7, v3
	v_add_f32_e32 v8, v8, v8
	v_add_f32_e32 v9, v9, v9
	v_mul_f32_e32 v6, 0x3f4c422a, v6
	v_mul_f32_e32 v7, 0x3f4c422a, v7
	v_mul_f32_e32 v8, 0x3fb8aa3b, v8
	v_mul_f32_e32 v9, 0x3fb8aa3b, v9
	v_add_f32_e32 v6, v6, v6
	v_add_f32_e32 v7, v7, v7
	v_exp_f32_e32 v8, v8
	v_exp_f32_e32 v9, v9
	v_mul_f32_e32 v6, 0x3fb8aa3b, v6
	v_mul_f32_e32 v7, 0x3fb8aa3b, v7
	v_exp_f32_e32 v6, v6
	v_exp_f32_e32 v7, v7
	v_add_f32_e32 v4, 1.0, v8
	v_add_f32_e32 v5, 1.0, v9
	v_rcp_f32_e32 v4, v4
	v_rcp_f32_e32 v5, v5
	v_add_f32_e32 v6, 1.0, v6
	v_add_f32_e32 v7, 1.0, v7
	v_rcp_f32_e32 v6, v6
	v_rcp_f32_e32 v7, v7
	v_pk_add_f32 v[4:5], v[4:5], 1.0 op_sel_hi:[1,0] neg_lo:[1,0] neg_hi:[1,0]
	s_nop 0
	v_pk_mul_f32 v[0:1], v[0:1], v[4:5]
	v_pk_add_f32 v[4:5], v[6:7], 1.0 op_sel_hi:[1,0] neg_lo:[1,0] neg_hi:[1,0]
	v_cvt_pk_bf16_f32 v0, v0, v1
	v_pk_mul_f32 v[2:3], v[2:3], v[4:5]
	s_nop 0
	v_cvt_pk_bf16_f32 v1, v2, v3
	v_lshl_add_u64 v[2:3], v[14:15], 0, v[112:113]
	v_lshl_add_u64 v[2:3], v[2:3], 0, s[74:75]
	v_lshl_add_u64 v[2:3], v[2:3], 0, v[160:161]
	global_store_dwordx2 v[2:3], v[0:1], off sc0 sc1
	s_waitcnt vmcnt(0)
	s_barrier
.LBB0_1079:
	v_readlane_b32 s0, v253, 0
	v_readlane_b32 s1, v253, 2
	s_nop 3
	s_cmp_lg_u32 s1, 0
	s_cbranch_scc1 .Lmy_ya_noarr
	s_cmpk_lt_u32 s0, 0x40
	s_cbranch_scc0 .Lmy_ya_noarr
	v_mov_b32_e32 v0, 0x20518
	ds_read_b64 v[0:1], v0
	s_waitcnt lgkmcnt(0)
	v_readfirstlane_b32 s2, v0
	v_readfirstlane_b32 s3, v1
	s_and_b32 s0, s0, 3
	s_lshl_b32 s0, s0, 2
	s_addk_i32 s0, 0x180
	v_mov_b32_e32 v0, s0
	s_mov_b64 exec, 1
	v_mov_b32_e32 v1, 1
	s_nop 2
	global_atomic_add v0, v1, s[2:3]
	s_mov_b64 exec, -1
.Lmy_ya_noarr:
	s_add_i32 s22, s73, 3
	s_branch .LBB0_1133
	s_waitcnt vmcnt(0) lgkmcnt(0)
	v_cmp_eq_u32_e32 vcc, 0, v134
	s_waitcnt vmcnt(0)
	s_barrier
	s_and_saveexec_b64 s[0:1], vcc
	s_cbranch_execz .LBB0_1132
	v_readlane_b32 s3, v253, 8
	s_getreg_b32 s2, hwreg(HW_REG_XCC_ID, 0, 4)
	s_and_b32 s16, s2, 15
	v_mov_b32_e32 v0, s3
	ds_read_b32 v2, v0
	v_readlane_b32 s3, v253, 9
	s_waitcnt lgkmcnt(0)
	v_cmp_ne_u32_e32 vcc, 0, v2
	v_mov_b32_e32 v0, s3
	ds_read_b32 v0, v0
	s_cbranch_vccnz .LBB0_1096
	v_readlane_b32 s8, v253, 63
	v_readlane_b32 s9, v254, 0
	s_add_u32 s2, s8, 0x1000
	s_addc_u32 s3, s9, 0
	s_add_u32 s4, s8, 0x1100
	s_addc_u32 s5, s9, 0
	s_add_u32 s6, s8, 0x1200
	s_addc_u32 s7, s9, 0
	s_add_u32 s8, s8, 0x1300
	s_addc_u32 s9, s9, 0
	s_mov_b32 s17, 1
	s_branch .LBB0_1084

; #define PG8_STAGE(bufoff, gbase, voff) do { _Pragma("unroll") for (int _i = 0; _i < 2; ++_i) \
;         __builtin_amdgcn_global_load_lds((const unsigned*)((const char*)(gbase) + (voff)[_i]), (LAS unsigned*)(lds + (bufoff) + ldsw + _i * 8192), 16, 0, 0); } while (0)
; #define INP(i) ((const float*)ld_ptr(pb, (i)))
; template <class Epi, bool ALIGN_EPI>
; __device__ __forceinline__ void gemm_phase(LAS unsigned char* lds, const Gemm g, const Order& S, const Epi& E, const int wave_id) {
;     ...
;     for (int i = 0; i < 2; ++i) { int R, C; stage_rc(tid * 16 + i * 8192, R, C); const int Rb = Epi::PERM ? ((R & ~31) + perm32(R & 31)) : R; voffA[i] = (unsigned)(R * g.lda + C) * 2u; voffB[i] = (unsigned)(Rb * g.ldb + C) * 2u; }
;     const size_t kstep = (size_t)(BK * 2);
;     const size_t hstepA = (size_t)HALF * g.lda * 2, hstepB = (size_t)HALF * g.ldb * 2;
;     const unsigned ldsw = (unsigned)wid * 1024u;
;     const int aoff = lds_byte(wr * 64 + fr, fq * 8), boff = lds_byte(wc * 32 + fr, fq * 8);
;     ...
;     Unit cur, nxt; int ui = 0;
;     if (!S.next(0, cur)) return;
;     f32x4 acc[2][2][4][2];
; #pragma unroll
;     for (int a = 0; a < 2; ++a)
; #pragma unroll
;         for (int b = 0; b < 2; ++b)
; #pragma unroll
;             for (int m = 0; m < 4; ++m)
; #pragma unroll
;                 for (int n = 0; n < 2; ++n) acc[a][b][m][n] = (f32x4){0.f, 0.f, 0.f, 0.f};
;     bf16x8 At[4][2], B0[2][2], B1[2][2];
;     const char* cA = (const char*)g.A + (size_t)cur.z * g.sAz + (size_t)cur.pm * 2 * hstepA + (size_t)cur.k0 * 2; const char* cB = (const char*)g.Bt + (size_t)cur.z * g.sBz + (size_t)cur.pn * 2 * hstepB + (size_t)cur.k0 * 2;
;     PG8_STAGE(PG8_SB(0, 0), cB, voffB); PG8_STAGE(PG8_SB(0, 1), cB + hstepB, voffB); PG8_STAGE(PG8_SA(0, 0), cA, voffA); PG8_STAGE(PG8_SA(0, 1), cA + hstepA, voffA);
; __global__ void __launch_bounds__(512, 2) hybrid_fwd(Params P) {
;     ...
;             pg8::Gemm g{Zb, WGLU + (size_t)l * 65536, 256, 256, 256, 0, 0}; pg8::Order S; S.init(M / 256, 1, 1, G, bid, 4);
;             EpiGlu E{Zb, MIX, INP(24) + l * 256};
;             pg8::gemm_phase<EpiGlu, true>(ldsl, g, S, E, wave);
.LBB0_1141:
	s_lshr_b32 s9, s44, 3
	s_add_u32 s6, s2, 0x13200000
	s_addc_u32 s7, s3, 0
	s_lshl_b64 s[0:1], s[96:97], 17
	s_add_u32 s0, s2, s0
	s_addc_u32 s1, s3, s1
	s_add_u32 s45, s0, 0x1600000
	s_addc_u32 s46, s1, 0
	s_lshl_b32 s47, s12, 10
	v_lshl_add_u32 v0, v8, 4, s47
	v_ashrrev_i32_e32 v1, 31, v0
	v_lshrrev_b32_e32 v1, 22, v1
	v_add_u32_e32 v1, v0, v1
	v_ashrrev_i32_e32 v1, 10, v1
	v_mul_i32_i24_e32 v2, 0x400, v1
	v_sub_u32_e32 v2, v0, v2
	v_lshrrev_b32_e32 v3, 4, v2
	v_bitop3_b32 v2, v3, v2, 32 bitop3:0x6c
	v_ashrrev_i32_e32 v4, 31, v2
	v_lshrrev_b32_e32 v4, 26, v4
	v_add_u32_e32 v4, v2, v4
	v_lshrrev_b32_e32 v5, 6, v4
	v_and_b32_e32 v4, 0xc0, v4
	v_lshlrev_b32_e32 v3, 3, v1
	v_lshlrev_b32_e32 v1, 5, v1
	v_sub_u32_e32 v2, v2, v4
	v_and_b32_e32 v3, 0x7ffff0, v3
	v_and_b32_e32 v1, 32, v1
	v_ashrrev_i16_sdwa v2, v201, sext(v2) dst_sel:DWORD dst_unused:UNUSED_PAD src0_sel:DWORD src1_sel:BYTE_0
	v_add_u32_sdwa v1, v1, sext(v2) dst_sel:DWORD dst_unused:UNUSED_PAD src0_sel:DWORD src1_sel:WORD_0
	v_add_lshl_u32 v2, v5, v3, 9
	v_add_u32_e32 v0, 0x2000, v0
	v_lshl_add_u32 v160, v1, 1, v2
	v_ashrrev_i32_e32 v1, 31, v0
	v_lshrrev_b32_e32 v1, 22, v1
	v_add_u32_e32 v1, v0, v1
	v_ashrrev_i32_e32 v1, 10, v1
	v_mul_i32_i24_e32 v2, 0x400, v1
	v_sub_u32_e32 v0, v0, v2
	v_lshrrev_b32_e32 v2, 4, v0
	v_bitop3_b32 v0, v2, v0, 32 bitop3:0x6c
	v_ashrrev_i32_e32 v3, 31, v0
	v_lshrrev_b32_e32 v3, 26, v3
	v_add_u32_e32 v3, v0, v3
	v_lshrrev_b32_e32 v4, 6, v3
	v_and_b32_e32 v3, 0xffc0, v3
	v_sub_u32_e32 v0, v0, v3
	v_lshrrev_b16_e32 v3, 7, v0
	s_add_i32 s0, s8, s9
	v_and_b32_e32 v3, 1, v3
	s_and_b32 s1, s0, 0xf8
	v_lshlrev_b32_e32 v2, 3, v1
	v_lshlrev_b32_e32 v1, 5, v1
	v_add_u16_e32 v0, v0, v3
	s_sub_i32 s8, 0x42, s1
	v_and_b32_e32 v2, 0x7ffff0, v2
	v_and_b32_e32 v1, 32, v1
	v_ashrrev_i16_sdwa v0, v201, sext(v0) dst_sel:DWORD dst_unused:UNUSED_PAD src0_sel:DWORD src1_sel:BYTE_0
	s_min_u32 s13, s8, 8
	v_add_u32_sdwa v0, v1, sext(v0) dst_sel:DWORD dst_unused:UNUSED_PAD src0_sel:DWORD src1_sel:WORD_0
	v_add_lshl_u32 v1, v4, v2, 9
	v_cvt_f32_ubyte0_e32 v2, s13
	v_rcp_iflag_f32_e32 v3, v2
	s_and_b32 s14, s0, 7
	v_lshl_add_u32 v128, v0, 1, v1
	v_cvt_f32_ubyte0_e32 v0, s14
	v_mul_f32_e32 v1, v0, v3
	v_trunc_f32_e32 v1, v1
	v_cvt_u32_f32_e32 v3, v1
	v_fma_f32 v0, -v1, v2, v0
	s_ashr_i32 s0, s12, 2
	v_cmp_ge_f32_e64 s[8:9], |v0|, v2
	v_readfirstlane_b32 s15, v3
	s_cmp_lg_u64 s[8:9], 0
	s_addc_u32 s8, s15, 0
	s_mul_i32 s9, s8, s13
	s_sub_i32 s9, s14, s9
	s_and_b32 s9, s9, 0xff
	s_or_b32 s58, s1, s9
	s_lshl_b32 s1, s58, 17
	s_add_u32 s22, s6, s1
	s_addc_u32 s23, s7, 0
	s_and_b32 s1, s8, 0xff
	s_lshl_b32 s1, s1, 17
	s_add_u32 s24, s45, s1
	s_addc_u32 s25, s46, 0
	s_add_i32 s48, s47, 0
	s_add_i32 m0, s48, 0x10000
	v_mov_b32_e32 v129, v161
	global_load_lds_dwordx4 v160, s[24:25]
	s_add_i32 m0, s48, 0x12000
	s_add_u32 s8, s24, 0x10000
	global_load_lds_dwordx4 v128, s[24:25]
	s_addc_u32 s9, s25, 0
	s_add_i32 m0, s48, 0x14000
	s_add_i32 s49, s48, 0x2000
	global_load_lds_dwordx4 v160, s[8:9]
	s_add_i32 m0, s48, 0x16000
	v_lshl_add_u64 v[6:7], s[24:25], 0, v[160:161]
	global_load_lds_dwordx4 v128, s[8:9]
	s_lshr_b32 s13, s58, 4
	s_lshl_b32 s13, s13, 2
	s_addk_i32 s13, 0x180
	s_lshl_b32 s14, s96, 4
	s_add_i32 s14, s14, 16
	s_mul_i32 s15, s96, 0xc0
	s_addk_i32 s15, 0xc0
	s_cmp_lt_u32 s58, 64
	s_cselect_b32 s13, s13, 0x190
	s_cselect_b32 s14, s14, s15
	s_add_u32 s8, s2, s13
	s_addc_u32 s9, s3, 0
	s_mov_b32 s15, 0
.Lmy_yg_poll:
	v_mov_b32_e32 v255, 0
	global_load_dword v255, v255, s[8:9] sc0 sc1
	s_waitcnt vmcnt(0)
	v_readfirstlane_b32 s13, v255
	s_cmp_ge_u32 s13, s14
	s_cbranch_scc1 .Lmy_yg_ok
	s_add_i32 s15, s15, 1
	s_cmp_lt_u32 s15, 0x800
	s_cbranch_scc0 .Lmy_yg_ok
	s_sleep 1
	s_branch .Lmy_yg_poll
.Lmy_yg_ok:
	s_mov_b32 m0, s48
	s_add_u32 s8, s22, 0x10000
	global_load_lds_dwordx4 v160, s[22:23]
	s_mov_b32 m0, s49
	s_addc_u32 s9, s23, 0
	s_add_i32 s50, s48, 0x4000
	global_load_lds_dwordx4 v128, s[22:23]
	s_mov_b32 m0, s50
	s_add_i32 s51, s48, 0x6000
	global_load_lds_dwordx4 v160, s[8:9]
	s_mov_b32 m0, s51
	s_cmp_eq_u32 s0, 1
	global_load_lds_dwordx4 v128, s[8:9]
	v_lshl_add_u64 v[4:5], s[24:25], 0, v[128:129]
	v_lshl_add_u64 v[0:1], s[22:23], 0, v[160:161]
	s_cselect_b64 s[8:9], -1, 0
	s_cmp_lg_u32 s0, 1
	v_lshl_add_u64 v[2:3], s[22:23], 0, v[128:129]
	s_cbranch_scc1 .LBB0_1143
	s_barrier
